# GEMM K loops: one static s_setprio 1 for waves 4..7 (the wave row that arrives second), per-segment priority toggles removed
# speedup vs baseline: 1.0271x; 1.0010x over previous
.LBB0_120:
	s_ashr_i32 s55, s54, 31
	s_lshl_b64 s[56:57], s[54:55], 19
	s_add_u32 s56, s0, s56
	s_addc_u32 s57, s1, s57
	s_and_b64 s[58:59], s[18:19], exec
	s_cselect_b32 s55, s57, s67
	s_cselect_b32 s61, s56, s66
	s_ashr_i32 s51, s50, 31
	s_lshl_b64 s[58:59], s[50:51], 19
	s_add_u32 s58, s22, s58
	s_addc_u32 s59, s23, s59
	s_and_b64 s[68:69], s[18:19], exec
	s_cselect_b32 s51, s59, s65
	s_cselect_b32 s63, s58, s64
	s_add_u32 s84, s64, 0x100
	s_addc_u32 s85, s65, 0
	s_add_u32 s64, s66, 0x40080
	v_mov_b32_e32 v0, 0
	s_addc_u32 s65, s67, 0
	s_mov_b32 s86, -2
	v_mov_b32_e32 v1, v0
	v_mov_b32_e32 v2, v0
	v_mov_b32_e32 v3, v0
	v_mov_b32_e32 v8, v0
	v_mov_b32_e32 v9, v0
	v_mov_b32_e32 v10, v0
	v_mov_b32_e32 v11, v0
	v_mov_b32_e32 v16, v0
	v_mov_b32_e32 v17, v0
	v_mov_b32_e32 v18, v0
	v_mov_b32_e32 v19, v0
	v_mov_b32_e32 v24, v0
	v_mov_b32_e32 v25, v0
	v_mov_b32_e32 v26, v0
	v_mov_b32_e32 v27, v0
	v_mov_b32_e32 v32, v0
	v_mov_b32_e32 v33, v0
	v_mov_b32_e32 v34, v0
	v_mov_b32_e32 v35, v0
	v_mov_b32_e32 v52, v0
	v_mov_b32_e32 v53, v0
	v_mov_b32_e32 v54, v0
	v_mov_b32_e32 v55, v0
	v_mov_b32_e32 v60, v0
	v_mov_b32_e32 v61, v0
	v_mov_b32_e32 v62, v0
	v_mov_b32_e32 v63, v0
	v_mov_b32_e32 v68, v0
	v_mov_b32_e32 v69, v0
	v_mov_b32_e32 v70, v0
	v_mov_b32_e32 v71, v0
	v_mov_b32_e32 v12, v0
	v_mov_b32_e32 v13, v0
	v_mov_b32_e32 v14, v0
	v_mov_b32_e32 v15, v0
	v_mov_b32_e32 v4, v0
	v_mov_b32_e32 v5, v0
	v_mov_b32_e32 v6, v0
	v_mov_b32_e32 v7, v0
	v_mov_b32_e32 v28, v0
	v_mov_b32_e32 v29, v0
	v_mov_b32_e32 v30, v0
	v_mov_b32_e32 v31, v0
	v_mov_b32_e32 v20, v0
	v_mov_b32_e32 v21, v0
	v_mov_b32_e32 v22, v0
	v_mov_b32_e32 v23, v0
	v_mov_b32_e32 v56, v0
	v_mov_b32_e32 v57, v0
	v_mov_b32_e32 v58, v0
	v_mov_b32_e32 v59, v0
	v_mov_b32_e32 v36, v0
	v_mov_b32_e32 v37, v0
	v_mov_b32_e32 v38, v0
	v_mov_b32_e32 v39, v0
	v_mov_b32_e32 v72, v0
	v_mov_b32_e32 v73, v0
	v_mov_b32_e32 v74, v0
	v_mov_b32_e32 v75, v0
	v_mov_b32_e32 v64, v0
	v_mov_b32_e32 v65, v0
	v_mov_b32_e32 v66, v0
	v_mov_b32_e32 v67, v0
	v_mov_b32_e32 v76, v0
	v_mov_b32_e32 v77, v0
	v_mov_b32_e32 v78, v0
	v_mov_b32_e32 v79, v0
	v_mov_b32_e32 v84, v0
	v_mov_b32_e32 v85, v0
	v_mov_b32_e32 v86, v0
	v_mov_b32_e32 v87, v0
	v_mov_b32_e32 v92, v0
	v_mov_b32_e32 v93, v0
	v_mov_b32_e32 v94, v0
	v_mov_b32_e32 v95, v0
	v_mov_b32_e32 v100, v0
	v_mov_b32_e32 v101, v0
	v_mov_b32_e32 v102, v0
	v_mov_b32_e32 v103, v0
	v_mov_b32_e32 v108, v0
	v_mov_b32_e32 v109, v0
	v_mov_b32_e32 v110, v0
	v_mov_b32_e32 v111, v0
	v_mov_b32_e32 v116, v0
	v_mov_b32_e32 v117, v0
	v_mov_b32_e32 v118, v0
	v_mov_b32_e32 v119, v0
	v_mov_b32_e32 v124, v0
	v_mov_b32_e32 v125, v0
	v_mov_b32_e32 v126, v0
	v_mov_b32_e32 v127, v0
	v_mov_b32_e32 v132, v0
	v_mov_b32_e32 v133, v0
	v_mov_b32_e32 v134, v0
	v_mov_b32_e32 v135, v0
	v_mov_b32_e32 v88, v0
	v_mov_b32_e32 v89, v0
	v_mov_b32_e32 v90, v0
	v_mov_b32_e32 v91, v0
	v_mov_b32_e32 v80, v0
	v_mov_b32_e32 v81, v0
	v_mov_b32_e32 v82, v0
	v_mov_b32_e32 v83, v0
	v_mov_b32_e32 v104, v0
	v_mov_b32_e32 v105, v0
	v_mov_b32_e32 v106, v0
	v_mov_b32_e32 v107, v0
	v_mov_b32_e32 v96, v0
	v_mov_b32_e32 v97, v0
	v_mov_b32_e32 v98, v0
	v_mov_b32_e32 v99, v0
	v_mov_b32_e32 v120, v0
	v_mov_b32_e32 v121, v0
	v_mov_b32_e32 v122, v0
	v_mov_b32_e32 v123, v0
	v_mov_b32_e32 v112, v0
	v_mov_b32_e32 v113, v0
	v_mov_b32_e32 v114, v0
	v_mov_b32_e32 v115, v0
	v_mov_b32_e32 v136, v0
	v_mov_b32_e32 v137, v0
	v_mov_b32_e32 v138, v0
	v_mov_b32_e32 v139, v0
	v_mov_b32_e32 v128, v0
	v_mov_b32_e32 v129, v0
	v_mov_b32_e32 v130, v0
	v_mov_b32_e32 v131, v0
	v_readfirstlane_b32 s99, v201
	s_cmp_lt_u32 s99, 0x100
	s_cbranch_scc1 .Lprio_skip0
	s_setprio 1
.Lprio_skip0:
.LBB0_121:
	ds_read_b128 v[40:43], v168
	ds_read_b128 v[44:47], v168 offset:1024
	ds_read_b128 v[48:51], v168 offset:2048
	ds_read_b128 v[140:143], v168 offset:3072
	ds_read_b128 v[172:175], v169
	ds_read_b128 v[176:179], v169 offset:1024
	ds_read_b128 v[180:183], v169 offset:2048
	ds_read_b128 v[184:187], v169 offset:3072
	s_add_u32 s66, s64, 0xfffc0080
	s_addc_u32 s67, s65, -1
	s_cmp_eq_u32 s86, 12
	s_cselect_b32 s69, s55, s67
	s_cselect_b32 s68, s61, s66
	s_cselect_b32 s67, s51, s85
	s_cselect_b32 s66, s63, s84
	v_lshl_add_u64 v[158:159], s[64:65], 0, v[152:153]
	s_add_i32 m0, s53, 0xc000
	ds_read_b128 v[188:191], v170
	ds_read_b128 v[192:195], v170 offset:1024
	ds_read_b128 v[196:199], v170 offset:2048
	ds_read_b128 v[210:213], v170 offset:3072
	ds_read_b128 v[214:217], v170 offset:4096
	ds_read_b128 v[218:221], v170 offset:5120
	ds_read_b128 v[222:225], v170 offset:6144
	ds_read_b128 v[226:229], v170 offset:7168
	global_load_lds_dwordx4 v[158:159], off
	v_lshl_add_u64 v[158:159], s[64:65], 0, v[150:151]
	s_add_i32 m0, s53, 0xe000
	s_nop 0
	global_load_lds_dwordx4 v[158:159], off
	s_waitcnt vmcnt(8)
	s_waitcnt lgkmcnt(0)
	s_barrier
	s_waitcnt lgkmcnt(0)
	v_mfma_f32_16x16x32_bf16 v[128:131], v[40:43], v[188:191], v[128:131]
	v_mfma_f32_16x16x32_bf16 v[136:139], v[48:51], v[188:191], v[136:139]
	v_mfma_f32_16x16x32_bf16 v[112:115], v[40:43], v[196:199], v[112:115]
	v_mfma_f32_16x16x32_bf16 v[120:123], v[48:51], v[196:199], v[120:123]
	v_mfma_f32_16x16x32_bf16 v[96:99], v[40:43], v[214:217], v[96:99]
	v_mfma_f32_16x16x32_bf16 v[104:107], v[48:51], v[214:217], v[104:107]
	v_mfma_f32_16x16x32_bf16 v[80:83], v[40:43], v[222:225], v[80:83]
	v_mfma_f32_16x16x32_bf16 v[88:91], v[48:51], v[222:225], v[88:91]
	v_mfma_f32_16x16x32_bf16 v[128:131], v[44:47], v[192:195], v[128:131]
	v_mfma_f32_16x16x32_bf16 v[136:139], v[140:143], v[192:195], v[136:139]
	v_mfma_f32_16x16x32_bf16 v[112:115], v[44:47], v[210:213], v[112:115]
	v_mfma_f32_16x16x32_bf16 v[120:123], v[140:143], v[210:213], v[120:123]
	v_mfma_f32_16x16x32_bf16 v[96:99], v[44:47], v[218:221], v[96:99]
	v_mfma_f32_16x16x32_bf16 v[104:107], v[140:143], v[218:221], v[104:107]
	v_mfma_f32_16x16x32_bf16 v[80:83], v[44:47], v[226:229], v[80:83]
	v_mfma_f32_16x16x32_bf16 v[88:91], v[140:143], v[226:229], v[88:91]
	v_mfma_f32_16x16x32_bf16 v[132:135], v[172:175], v[188:191], v[132:135]
	v_mfma_f32_16x16x32_bf16 v[124:127], v[180:183], v[188:191], v[124:127]
	v_mfma_f32_16x16x32_bf16 v[116:119], v[172:175], v[196:199], v[116:119]
	v_mfma_f32_16x16x32_bf16 v[108:111], v[180:183], v[196:199], v[108:111]
	v_mfma_f32_16x16x32_bf16 v[100:103], v[172:175], v[214:217], v[100:103]
	v_mfma_f32_16x16x32_bf16 v[92:95], v[180:183], v[214:217], v[92:95]
	v_mfma_f32_16x16x32_bf16 v[84:87], v[172:175], v[222:225], v[84:87]
	v_mfma_f32_16x16x32_bf16 v[76:79], v[180:183], v[222:225], v[76:79]
	v_mfma_f32_16x16x32_bf16 v[132:135], v[176:179], v[192:195], v[132:135]
	v_mfma_f32_16x16x32_bf16 v[124:127], v[184:187], v[192:195], v[124:127]
	v_mfma_f32_16x16x32_bf16 v[116:119], v[176:179], v[210:213], v[116:119]
	v_mfma_f32_16x16x32_bf16 v[108:111], v[184:187], v[210:213], v[108:111]
	v_mfma_f32_16x16x32_bf16 v[100:103], v[176:179], v[218:221], v[100:103]
	v_mfma_f32_16x16x32_bf16 v[92:95], v[184:187], v[218:221], v[92:95]
	v_mfma_f32_16x16x32_bf16 v[84:87], v[176:179], v[226:229], v[84:87]
	v_mfma_f32_16x16x32_bf16 v[76:79], v[184:187], v[226:229], v[76:79]
	s_barrier
	s_add_i32 s87, s81, s3
	v_lshl_add_u64 v[158:159], s[66:67], 0, v[144:145]
	s_mov_b32 m0, s87
	ds_read_b128 v[188:191], v170 offset:16384
	ds_read_b128 v[192:195], v170 offset:17408
	ds_read_b128 v[196:199], v170 offset:18432
	ds_read_b128 v[210:213], v170 offset:19456
	ds_read_b128 v[214:217], v170 offset:20480
	ds_read_b128 v[218:221], v170 offset:21504
	ds_read_b128 v[222:225], v170 offset:22528
	ds_read_b128 v[226:229], v170 offset:23552
	global_load_lds_dwordx4 v[158:159], off
	s_add_i32 m0, s87, 0x2000
	s_add_u32 s88, s66, 0x40000
	v_lshl_add_u64 v[230:231], s[66:67], 0, v[146:147]
	s_addc_u32 s89, s67, 0
	s_add_i32 s87, s82, s3
	global_load_lds_dwordx4 v[230:231], off
	v_lshl_add_u64 v[232:233], s[88:89], 0, v[144:145]
	s_mov_b32 m0, s87
	v_lshl_add_u64 v[234:235], s[68:69], 0, v[146:147]
	global_load_lds_dwordx4 v[232:233], off
	v_lshl_add_u64 v[232:233], s[88:89], 0, v[146:147]
	s_add_i32 m0, s87, 0x2000
	s_nop 0
	global_load_lds_dwordx4 v[232:233], off
	v_lshl_add_u64 v[232:233], s[68:69], 0, v[144:145]
	s_mov_b32 m0, s53
	s_nop 0
	global_load_lds_dwordx4 v[232:233], off
	s_mov_b32 m0, s70
	s_nop 0
	global_load_lds_dwordx4 v[234:235], off
	s_waitcnt vmcnt(8)
	s_waitcnt lgkmcnt(0)
	s_barrier
	s_waitcnt lgkmcnt(0)
	v_mfma_f32_16x16x32_bf16 v[64:67], v[40:43], v[188:191], v[64:67]
	v_mfma_f32_16x16x32_bf16 v[72:75], v[48:51], v[188:191], v[72:75]
	v_mfma_f32_16x16x32_bf16 v[36:39], v[40:43], v[196:199], v[36:39]
	v_mfma_f32_16x16x32_bf16 v[56:59], v[48:51], v[196:199], v[56:59]
	v_mfma_f32_16x16x32_bf16 v[20:23], v[40:43], v[214:217], v[20:23]
	v_mfma_f32_16x16x32_bf16 v[28:31], v[48:51], v[214:217], v[28:31]
	v_mfma_f32_16x16x32_bf16 v[4:7], v[40:43], v[222:225], v[4:7]
	v_mfma_f32_16x16x32_bf16 v[12:15], v[48:51], v[222:225], v[12:15]
	v_mfma_f32_16x16x32_bf16 v[64:67], v[44:47], v[192:195], v[64:67]
	v_mfma_f32_16x16x32_bf16 v[72:75], v[140:143], v[192:195], v[72:75]
	v_mfma_f32_16x16x32_bf16 v[36:39], v[44:47], v[210:213], v[36:39]
	v_mfma_f32_16x16x32_bf16 v[56:59], v[140:143], v[210:213], v[56:59]
	v_mfma_f32_16x16x32_bf16 v[20:23], v[44:47], v[218:221], v[20:23]
	v_mfma_f32_16x16x32_bf16 v[28:31], v[140:143], v[218:221], v[28:31]
	v_mfma_f32_16x16x32_bf16 v[4:7], v[44:47], v[226:229], v[4:7]
	v_mfma_f32_16x16x32_bf16 v[12:15], v[140:143], v[226:229], v[12:15]
	v_mfma_f32_16x16x32_bf16 v[32:35], v[180:183], v[196:199], v[32:35]
	v_mfma_f32_16x16x32_bf16 v[24:27], v[172:175], v[214:217], v[24:27]
	v_mfma_f32_16x16x32_bf16 v[16:19], v[180:183], v[214:217], v[16:19]
	v_mfma_f32_16x16x32_bf16 v[8:11], v[172:175], v[222:225], v[8:11]
	v_mfma_f32_16x16x32_bf16 v[0:3], v[180:183], v[222:225], v[0:3]
	v_mfma_f32_16x16x32_bf16 v[40:43], v[172:175], v[188:191], v[68:71]
	v_mfma_f32_16x16x32_bf16 v[44:47], v[180:183], v[188:191], v[60:63]
	v_mfma_f32_16x16x32_bf16 v[48:51], v[172:175], v[196:199], v[52:55]
	v_mfma_f32_16x16x32_bf16 v[32:35], v[184:187], v[210:213], v[32:35]
	v_mfma_f32_16x16x32_bf16 v[24:27], v[176:179], v[218:221], v[24:27]
	v_mfma_f32_16x16x32_bf16 v[16:19], v[184:187], v[218:221], v[16:19]
	v_mfma_f32_16x16x32_bf16 v[8:11], v[176:179], v[226:229], v[8:11]
	v_mfma_f32_16x16x32_bf16 v[0:3], v[184:187], v[226:229], v[0:3]
	v_mfma_f32_16x16x32_bf16 v[40:43], v[176:179], v[192:195], v[40:43]
	v_mfma_f32_16x16x32_bf16 v[44:47], v[184:187], v[192:195], v[44:47]
	v_mfma_f32_16x16x32_bf16 v[48:51], v[176:179], v[210:213], v[48:51]
	s_barrier
	s_add_i32 s87, 0, 0x18000
	s_add_i32 s88, 0, 0x1c000
	v_add_u32_e32 v140, s87, v161
	v_add_u32_e32 v148, s88, v161
	ds_read_b128 v[52:55], v140
	ds_read_b128 v[60:63], v140 offset:1024
	ds_read_b128 v[68:71], v140 offset:2048
	ds_read_b128 v[140:143], v140 offset:3072
	ds_read_b128 v[172:175], v148
	ds_read_b128 v[176:179], v148 offset:1024
	ds_read_b128 v[180:183], v148 offset:2048
	ds_read_b128 v[184:187], v148 offset:3072
	s_add_u32 s68, s68, 0x40000
	s_addc_u32 s69, s69, 0
	s_mov_b32 m0, s71
	v_lshl_add_u64 v[236:237], s[68:69], 0, v[144:145]
	ds_read_b128 v[188:191], v170 offset:32768
	ds_read_b128 v[192:195], v170 offset:33792
	ds_read_b128 v[196:199], v170 offset:34816
	ds_read_b128 v[210:213], v170 offset:35840
	ds_read_b128 v[214:217], v170 offset:36864
	ds_read_b128 v[218:221], v170 offset:37888
	ds_read_b128 v[222:225], v170 offset:38912
	ds_read_b128 v[226:229], v170 offset:39936
	global_load_lds_dwordx4 v[236:237], off
	v_lshl_add_u64 v[236:237], s[68:69], 0, v[146:147]
	s_mov_b32 m0, s72
	s_nop 0
	global_load_lds_dwordx4 v[236:237], off
	s_waitcnt vmcnt(8)
	s_waitcnt lgkmcnt(0)
	s_barrier
	s_waitcnt lgkmcnt(0)
	v_mfma_f32_16x16x32_bf16 v[128:131], v[52:55], v[188:191], v[128:131]
	v_mfma_f32_16x16x32_bf16 v[136:139], v[68:71], v[188:191], v[136:139]
	v_mfma_f32_16x16x32_bf16 v[112:115], v[52:55], v[196:199], v[112:115]
	v_mfma_f32_16x16x32_bf16 v[120:123], v[68:71], v[196:199], v[120:123]
	v_mfma_f32_16x16x32_bf16 v[96:99], v[52:55], v[214:217], v[96:99]
	v_mfma_f32_16x16x32_bf16 v[104:107], v[68:71], v[214:217], v[104:107]
	v_mfma_f32_16x16x32_bf16 v[80:83], v[52:55], v[222:225], v[80:83]
	v_mfma_f32_16x16x32_bf16 v[88:91], v[68:71], v[222:225], v[88:91]
	v_mfma_f32_16x16x32_bf16 v[128:131], v[60:63], v[192:195], v[128:131]
	v_mfma_f32_16x16x32_bf16 v[136:139], v[140:143], v[192:195], v[136:139]
	v_mfma_f32_16x16x32_bf16 v[112:115], v[60:63], v[210:213], v[112:115]
	v_mfma_f32_16x16x32_bf16 v[120:123], v[140:143], v[210:213], v[120:123]
	v_mfma_f32_16x16x32_bf16 v[96:99], v[60:63], v[218:221], v[96:99]
	v_mfma_f32_16x16x32_bf16 v[104:107], v[140:143], v[218:221], v[104:107]
	v_mfma_f32_16x16x32_bf16 v[80:83], v[60:63], v[226:229], v[80:83]
	v_mfma_f32_16x16x32_bf16 v[88:91], v[140:143], v[226:229], v[88:91]
	v_mfma_f32_16x16x32_bf16 v[132:135], v[172:175], v[188:191], v[132:135]
	v_mfma_f32_16x16x32_bf16 v[124:127], v[180:183], v[188:191], v[124:127]
	v_mfma_f32_16x16x32_bf16 v[116:119], v[172:175], v[196:199], v[116:119]
	v_mfma_f32_16x16x32_bf16 v[108:111], v[180:183], v[196:199], v[108:111]
	v_mfma_f32_16x16x32_bf16 v[100:103], v[172:175], v[214:217], v[100:103]
	v_mfma_f32_16x16x32_bf16 v[92:95], v[180:183], v[214:217], v[92:95]
	v_mfma_f32_16x16x32_bf16 v[84:87], v[172:175], v[222:225], v[84:87]
	v_mfma_f32_16x16x32_bf16 v[76:79], v[180:183], v[222:225], v[76:79]
	v_mfma_f32_16x16x32_bf16 v[132:135], v[176:179], v[192:195], v[132:135]
	v_mfma_f32_16x16x32_bf16 v[124:127], v[184:187], v[192:195], v[124:127]
	v_mfma_f32_16x16x32_bf16 v[116:119], v[176:179], v[210:213], v[116:119]
	v_mfma_f32_16x16x32_bf16 v[108:111], v[184:187], v[210:213], v[108:111]
	v_mfma_f32_16x16x32_bf16 v[100:103], v[176:179], v[218:221], v[100:103]
	v_mfma_f32_16x16x32_bf16 v[92:95], v[184:187], v[218:221], v[92:95]
	v_mfma_f32_16x16x32_bf16 v[84:87], v[176:179], v[226:229], v[84:87]
	v_mfma_f32_16x16x32_bf16 v[76:79], v[184:187], v[226:229], v[76:79]
	s_barrier
	s_add_i32 s68, s87, s3
	v_lshl_add_u64 v[158:159], v[158:159], 0, s[38:39]
	s_mov_b32 m0, s68
	ds_read_b128 v[188:191], v170 offset:49152
	ds_read_b128 v[192:195], v170 offset:50176
	ds_read_b128 v[196:199], v170 offset:51200
	ds_read_b128 v[210:213], v170 offset:52224
	ds_read_b128 v[214:217], v170 offset:53248
	ds_read_b128 v[218:221], v170 offset:54272
	ds_read_b128 v[222:225], v170 offset:55296
	ds_read_b128 v[226:229], v170 offset:56320
	global_load_lds_dwordx4 v[158:159], off
	s_add_i32 m0, s68, 0x2000
	s_add_u32 s66, s66, 0x40080
	v_lshl_add_u64 v[158:159], v[230:231], 0, s[38:39]
	s_addc_u32 s67, s67, 0
	s_add_i32 s68, s88, s3
	global_load_lds_dwordx4 v[158:159], off
	v_lshl_add_u64 v[158:159], s[66:67], 0, v[144:145]
	s_mov_b32 m0, s68
	s_nop 0
	global_load_lds_dwordx4 v[158:159], off
	v_lshl_add_u64 v[158:159], s[66:67], 0, v[146:147]
	s_add_i32 m0, s68, 0x2000
	s_nop 0
	global_load_lds_dwordx4 v[158:159], off
	v_lshl_add_u64 v[158:159], v[232:233], 0, s[38:39]
	s_mov_b32 m0, s76
	s_nop 0
	global_load_lds_dwordx4 v[158:159], off
	v_lshl_add_u64 v[158:159], v[234:235], 0, s[38:39]
	s_mov_b32 m0, s77
	s_nop 0
	global_load_lds_dwordx4 v[158:159], off
	s_waitcnt vmcnt(8)
	s_waitcnt lgkmcnt(0)
	s_barrier
	s_waitcnt lgkmcnt(0)
	v_mfma_f32_16x16x32_bf16 v[64:67], v[52:55], v[188:191], v[64:67]
	v_mfma_f32_16x16x32_bf16 v[72:75], v[68:71], v[188:191], v[72:75]
	v_mfma_f32_16x16x32_bf16 v[36:39], v[52:55], v[196:199], v[36:39]
	v_mfma_f32_16x16x32_bf16 v[56:59], v[68:71], v[196:199], v[56:59]
	v_mfma_f32_16x16x32_bf16 v[20:23], v[52:55], v[214:217], v[20:23]
	v_mfma_f32_16x16x32_bf16 v[28:31], v[68:71], v[214:217], v[28:31]
	v_mfma_f32_16x16x32_bf16 v[4:7], v[52:55], v[222:225], v[4:7]
	v_mfma_f32_16x16x32_bf16 v[12:15], v[68:71], v[222:225], v[12:15]
	v_mfma_f32_16x16x32_bf16 v[64:67], v[60:63], v[192:195], v[64:67]
	v_mfma_f32_16x16x32_bf16 v[72:75], v[140:143], v[192:195], v[72:75]
	v_mfma_f32_16x16x32_bf16 v[36:39], v[60:63], v[210:213], v[36:39]
	v_mfma_f32_16x16x32_bf16 v[56:59], v[140:143], v[210:213], v[56:59]
	v_mfma_f32_16x16x32_bf16 v[20:23], v[60:63], v[218:221], v[20:23]
	v_mfma_f32_16x16x32_bf16 v[28:31], v[140:143], v[218:221], v[28:31]
	v_mfma_f32_16x16x32_bf16 v[4:7], v[60:63], v[226:229], v[4:7]
	v_mfma_f32_16x16x32_bf16 v[12:15], v[140:143], v[226:229], v[12:15]
	v_mfma_f32_16x16x32_bf16 v[40:43], v[172:175], v[188:191], v[40:43]
	v_mfma_f32_16x16x32_bf16 v[68:71], v[176:179], v[192:195], v[40:43]
	v_mfma_f32_16x16x32_bf16 v[40:43], v[180:183], v[188:191], v[44:47]
	v_mfma_f32_16x16x32_bf16 v[60:63], v[184:187], v[192:195], v[40:43]
	v_mfma_f32_16x16x32_bf16 v[40:43], v[172:175], v[196:199], v[48:51]
	v_mfma_f32_16x16x32_bf16 v[32:35], v[180:183], v[196:199], v[32:35]
	v_mfma_f32_16x16x32_bf16 v[24:27], v[172:175], v[214:217], v[24:27]
	v_mfma_f32_16x16x32_bf16 v[16:19], v[180:183], v[214:217], v[16:19]
	v_mfma_f32_16x16x32_bf16 v[8:11], v[172:175], v[222:225], v[8:11]
	v_mfma_f32_16x16x32_bf16 v[0:3], v[180:183], v[222:225], v[0:3]
	v_mfma_f32_16x16x32_bf16 v[52:55], v[176:179], v[210:213], v[40:43]
	v_mfma_f32_16x16x32_bf16 v[32:35], v[184:187], v[210:213], v[32:35]
	v_mfma_f32_16x16x32_bf16 v[24:27], v[176:179], v[218:221], v[24:27]
	v_mfma_f32_16x16x32_bf16 v[16:19], v[184:187], v[218:221], v[16:19]
	v_mfma_f32_16x16x32_bf16 v[8:11], v[176:179], v[226:229], v[8:11]
	v_mfma_f32_16x16x32_bf16 v[0:3], v[184:187], v[226:229], v[0:3]
	s_barrier
	s_add_i32 s86, s86, 2
	s_add_u32 s84, s84, 0x100
	s_addc_u32 s85, s85, 0
	s_add_u32 s64, s64, 0x100
	s_addc_u32 s65, s65, 0
	s_cmp_gt_u32 s86, 13
	s_cbranch_scc0 .LBB0_121
	s_setprio 0
	s_and_b64 vcc, exec, s[40:41]
	s_cbranch_vccz .LBB0_124
	s_barrier

.LBB0_298:
	s_ashr_i32 s31, s30, 31
	s_lshl_b64 s[34:35], s[30:31], 20
	s_add_u32 s34, s10, s34
	s_addc_u32 s35, s11, s35
	s_and_b64 s[36:37], s[8:9], exec
	s_cselect_b32 s31, s35, s45
	s_cselect_b32 s39, s34, s44
	s_ashr_i32 s29, s28, 31
	s_lshl_b64 s[36:37], s[28:29], 20
	s_add_u32 s36, s0, s36
	s_addc_u32 s37, s1, s37
	s_and_b64 s[46:47], s[8:9], exec
	s_cselect_b32 s29, s37, s43
	s_cselect_b32 s41, s36, s42
	s_add_u32 s59, s42, 0x100
	s_addc_u32 s60, s43, 0
	s_add_u32 s42, s44, 0x80080
	v_mov_b32_e32 v0, 0
	s_addc_u32 s43, s45, 0
	s_mov_b32 s61, -2
	s_waitcnt lgkmcnt(0)
	v_mov_b32_e32 v1, v0
	v_mov_b32_e32 v2, v0
	v_mov_b32_e32 v3, v0
	v_mov_b32_e32 v4, v0
	v_mov_b32_e32 v5, v0
	v_mov_b32_e32 v6, v0
	v_mov_b32_e32 v7, v0
	v_mov_b32_e32 v16, v0
	v_mov_b32_e32 v17, v0
	v_mov_b32_e32 v18, v0
	v_mov_b32_e32 v19, v0
	v_mov_b32_e32 v20, v0
	v_mov_b32_e32 v21, v0
	v_mov_b32_e32 v22, v0
	v_mov_b32_e32 v23, v0
	v_mov_b32_e32 v32, v0
	v_mov_b32_e32 v33, v0
	v_mov_b32_e32 v34, v0
	v_mov_b32_e32 v35, v0
	v_mov_b32_e32 v36, v0
	v_mov_b32_e32 v37, v0
	v_mov_b32_e32 v38, v0
	v_mov_b32_e32 v39, v0
	v_mov_b32_e32 v48, v0
	v_mov_b32_e32 v49, v0
	v_mov_b32_e32 v50, v0
	v_mov_b32_e32 v51, v0
	v_mov_b32_e32 v52, v0
	v_mov_b32_e32 v53, v0
	v_mov_b32_e32 v54, v0
	v_mov_b32_e32 v55, v0
	v_mov_b32_e32 v8, v0
	v_mov_b32_e32 v9, v0
	v_mov_b32_e32 v10, v0
	v_mov_b32_e32 v11, v0
	v_mov_b32_e32 v12, v0
	v_mov_b32_e32 v13, v0
	v_mov_b32_e32 v14, v0
	v_mov_b32_e32 v15, v0
	v_mov_b32_e32 v24, v0
	v_mov_b32_e32 v25, v0
	v_mov_b32_e32 v26, v0
	v_mov_b32_e32 v27, v0
	v_mov_b32_e32 v28, v0
	v_mov_b32_e32 v29, v0
	v_mov_b32_e32 v30, v0
	v_mov_b32_e32 v31, v0
	v_mov_b32_e32 v40, v0
	v_mov_b32_e32 v41, v0
	v_mov_b32_e32 v42, v0
	v_mov_b32_e32 v43, v0
	v_mov_b32_e32 v44, v0
	v_mov_b32_e32 v45, v0
	v_mov_b32_e32 v46, v0
	v_mov_b32_e32 v47, v0
	v_mov_b32_e32 v56, v0
	v_mov_b32_e32 v57, v0
	v_mov_b32_e32 v58, v0
	v_mov_b32_e32 v59, v0
	v_mov_b32_e32 v60, v0
	v_mov_b32_e32 v61, v0
	v_mov_b32_e32 v62, v0
	v_mov_b32_e32 v63, v0
	v_mov_b32_e32 v64, v0
	v_mov_b32_e32 v65, v0
	v_mov_b32_e32 v66, v0
	v_mov_b32_e32 v67, v0
	v_mov_b32_e32 v68, v0
	v_mov_b32_e32 v69, v0
	v_mov_b32_e32 v70, v0
	v_mov_b32_e32 v71, v0
	v_mov_b32_e32 v80, v0
	v_mov_b32_e32 v81, v0
	v_mov_b32_e32 v82, v0
	v_mov_b32_e32 v83, v0
	v_mov_b32_e32 v84, v0
	v_mov_b32_e32 v85, v0
	v_mov_b32_e32 v86, v0
	v_mov_b32_e32 v87, v0
	v_mov_b32_e32 v96, v0
	v_mov_b32_e32 v97, v0
	v_mov_b32_e32 v98, v0
	v_mov_b32_e32 v99, v0
	v_mov_b32_e32 v100, v0
	v_mov_b32_e32 v101, v0
	v_mov_b32_e32 v102, v0
	v_mov_b32_e32 v103, v0
	v_mov_b32_e32 v112, v0
	v_mov_b32_e32 v113, v0
	v_mov_b32_e32 v114, v0
	v_mov_b32_e32 v115, v0
	v_mov_b32_e32 v116, v0
	v_mov_b32_e32 v117, v0
	v_mov_b32_e32 v118, v0
	v_mov_b32_e32 v119, v0
	v_mov_b32_e32 v72, v0
	v_mov_b32_e32 v73, v0
	v_mov_b32_e32 v74, v0
	v_mov_b32_e32 v75, v0
	v_mov_b32_e32 v76, v0
	v_mov_b32_e32 v77, v0
	v_mov_b32_e32 v78, v0
	v_mov_b32_e32 v79, v0
	v_mov_b32_e32 v88, v0
	v_mov_b32_e32 v89, v0
	v_mov_b32_e32 v90, v0
	v_mov_b32_e32 v91, v0
	v_mov_b32_e32 v92, v0
	v_mov_b32_e32 v93, v0
	v_mov_b32_e32 v94, v0
	v_mov_b32_e32 v95, v0
	v_mov_b32_e32 v104, v0
	v_mov_b32_e32 v105, v0
	v_mov_b32_e32 v106, v0
	v_mov_b32_e32 v107, v0
	v_mov_b32_e32 v108, v0
	v_mov_b32_e32 v109, v0
	v_mov_b32_e32 v110, v0
	v_mov_b32_e32 v111, v0
	v_mov_b32_e32 v120, v0
	v_mov_b32_e32 v121, v0
	v_mov_b32_e32 v122, v0
	v_mov_b32_e32 v123, v0
	v_mov_b32_e32 v124, v0
	v_mov_b32_e32 v125, v0
	v_mov_b32_e32 v126, v0
	v_mov_b32_e32 v127, v0
	v_readfirstlane_b32 s99, v201
	s_cmp_lt_u32 s99, 0x100
	s_cbranch_scc1 .Lprio_skip1
	s_setprio 1
.Lprio_skip1:
.LBB0_299:
	ds_read_b128 v[142:145], v155
	ds_read_b128 v[146:149], v155 offset:1024
	ds_read_b128 v[158:161], v155 offset:2048
	ds_read_b128 v[162:165], v155 offset:3072
	ds_read_b128 v[166:169], v156
	ds_read_b128 v[170:173], v156 offset:1024
	ds_read_b128 v[174:177], v156 offset:2048
	ds_read_b128 v[178:181], v156 offset:3072
	s_add_u32 s44, s42, 0xfff80080
	s_addc_u32 s45, s43, -1
	s_cmp_eq_u32 s61, 28
	s_cselect_b32 s47, s31, s45
	s_cselect_b32 s46, s39, s44
	s_cselect_b32 s45, s29, s60
	s_cselect_b32 s44, s41, s59
	v_lshl_add_u64 v[198:199], s[42:43], 0, v[136:137]
	s_add_i32 m0, s5, 0xc000
	ds_read_b128 v[182:185], v157
	ds_read_b128 v[186:189], v157 offset:1024
	ds_read_b128 v[190:193], v157 offset:2048
	ds_read_b128 v[194:197], v157 offset:3072
	ds_read_b128 v[210:213], v157 offset:4096
	ds_read_b128 v[214:217], v157 offset:5120
	ds_read_b128 v[218:221], v157 offset:6144
	ds_read_b128 v[222:225], v157 offset:7168
	global_load_lds_dwordx4 v[198:199], off
	v_lshl_add_u64 v[198:199], s[42:43], 0, v[134:135]
	s_add_i32 m0, s5, 0xe000
	s_nop 0
	global_load_lds_dwordx4 v[198:199], off
	s_waitcnt vmcnt(8)
	s_waitcnt lgkmcnt(0)
	s_barrier
	s_waitcnt lgkmcnt(0)
	v_mfma_f32_16x16x32_bf16 v[124:127], v[142:145], v[182:185], v[124:127]
	v_mfma_f32_16x16x32_bf16 v[120:123], v[158:161], v[182:185], v[120:123]
	v_mfma_f32_16x16x32_bf16 v[108:111], v[142:145], v[190:193], v[108:111]
	v_mfma_f32_16x16x32_bf16 v[104:107], v[158:161], v[190:193], v[104:107]
	v_mfma_f32_16x16x32_bf16 v[92:95], v[142:145], v[210:213], v[92:95]
	v_mfma_f32_16x16x32_bf16 v[88:91], v[158:161], v[210:213], v[88:91]
	v_mfma_f32_16x16x32_bf16 v[76:79], v[142:145], v[218:221], v[76:79]
	v_mfma_f32_16x16x32_bf16 v[72:75], v[158:161], v[218:221], v[72:75]
	v_mfma_f32_16x16x32_bf16 v[124:127], v[146:149], v[186:189], v[124:127]
	v_mfma_f32_16x16x32_bf16 v[120:123], v[162:165], v[186:189], v[120:123]
	v_mfma_f32_16x16x32_bf16 v[108:111], v[146:149], v[194:197], v[108:111]
	v_mfma_f32_16x16x32_bf16 v[104:107], v[162:165], v[194:197], v[104:107]
	v_mfma_f32_16x16x32_bf16 v[92:95], v[146:149], v[214:217], v[92:95]
	v_mfma_f32_16x16x32_bf16 v[88:91], v[162:165], v[214:217], v[88:91]
	v_mfma_f32_16x16x32_bf16 v[76:79], v[146:149], v[222:225], v[76:79]
	v_mfma_f32_16x16x32_bf16 v[72:75], v[162:165], v[222:225], v[72:75]
	v_mfma_f32_16x16x32_bf16 v[116:119], v[166:169], v[182:185], v[116:119]
	v_mfma_f32_16x16x32_bf16 v[112:115], v[174:177], v[182:185], v[112:115]
	v_mfma_f32_16x16x32_bf16 v[100:103], v[166:169], v[190:193], v[100:103]
	v_mfma_f32_16x16x32_bf16 v[96:99], v[174:177], v[190:193], v[96:99]
	v_mfma_f32_16x16x32_bf16 v[84:87], v[166:169], v[210:213], v[84:87]
	v_mfma_f32_16x16x32_bf16 v[80:83], v[174:177], v[210:213], v[80:83]
	v_mfma_f32_16x16x32_bf16 v[68:71], v[166:169], v[218:221], v[68:71]
	v_mfma_f32_16x16x32_bf16 v[64:67], v[174:177], v[218:221], v[64:67]
	v_mfma_f32_16x16x32_bf16 v[116:119], v[170:173], v[186:189], v[116:119]
	v_mfma_f32_16x16x32_bf16 v[112:115], v[178:181], v[186:189], v[112:115]
	v_mfma_f32_16x16x32_bf16 v[100:103], v[170:173], v[194:197], v[100:103]
	v_mfma_f32_16x16x32_bf16 v[96:99], v[178:181], v[194:197], v[96:99]
	v_mfma_f32_16x16x32_bf16 v[84:87], v[170:173], v[214:217], v[84:87]
	v_mfma_f32_16x16x32_bf16 v[80:83], v[178:181], v[214:217], v[80:83]
	v_mfma_f32_16x16x32_bf16 v[68:71], v[170:173], v[222:225], v[68:71]
	v_mfma_f32_16x16x32_bf16 v[64:67], v[178:181], v[222:225], v[64:67]
	s_barrier
	s_add_i32 s62, s56, s4
	v_lshl_add_u64 v[198:199], s[44:45], 0, v[128:129]
	s_mov_b32 m0, s62
	ds_read_b128 v[182:185], v157 offset:16384
	ds_read_b128 v[186:189], v157 offset:17408
	ds_read_b128 v[190:193], v157 offset:18432
	ds_read_b128 v[194:197], v157 offset:19456
	ds_read_b128 v[210:213], v157 offset:20480
	ds_read_b128 v[214:217], v157 offset:21504
	ds_read_b128 v[218:221], v157 offset:22528
	ds_read_b128 v[222:225], v157 offset:23552
	global_load_lds_dwordx4 v[198:199], off
	s_add_i32 m0, s62, 0x2000
	s_add_u32 s62, s44, 0x80000
	v_lshl_add_u64 v[226:227], s[44:45], 0, v[130:131]
	s_addc_u32 s63, s45, 0
	s_add_i32 s64, s57, s4
	global_load_lds_dwordx4 v[226:227], off
	v_lshl_add_u64 v[228:229], s[62:63], 0, v[128:129]
	s_mov_b32 m0, s64
	v_lshl_add_u64 v[230:231], s[46:47], 0, v[130:131]
	global_load_lds_dwordx4 v[228:229], off
	v_lshl_add_u64 v[228:229], s[62:63], 0, v[130:131]
	s_add_i32 m0, s64, 0x2000
	s_nop 0
	global_load_lds_dwordx4 v[228:229], off
	v_lshl_add_u64 v[228:229], s[46:47], 0, v[128:129]
	s_mov_b32 m0, s5
	s_nop 0
	global_load_lds_dwordx4 v[228:229], off
	s_mov_b32 m0, s48
	s_nop 0
	global_load_lds_dwordx4 v[230:231], off
	s_waitcnt vmcnt(8)
	s_waitcnt lgkmcnt(0)
	s_barrier
	s_waitcnt lgkmcnt(0)
	v_mfma_f32_16x16x32_bf16 v[60:63], v[142:145], v[182:185], v[60:63]
	v_mfma_f32_16x16x32_bf16 v[56:59], v[158:161], v[182:185], v[56:59]
	v_mfma_f32_16x16x32_bf16 v[44:47], v[142:145], v[190:193], v[44:47]
	v_mfma_f32_16x16x32_bf16 v[40:43], v[158:161], v[190:193], v[40:43]
	v_mfma_f32_16x16x32_bf16 v[28:31], v[142:145], v[210:213], v[28:31]
	v_mfma_f32_16x16x32_bf16 v[24:27], v[158:161], v[210:213], v[24:27]
	v_mfma_f32_16x16x32_bf16 v[12:15], v[142:145], v[218:221], v[12:15]
	v_mfma_f32_16x16x32_bf16 v[8:11], v[158:161], v[218:221], v[8:11]
	v_mfma_f32_16x16x32_bf16 v[60:63], v[146:149], v[186:189], v[60:63]
	v_mfma_f32_16x16x32_bf16 v[56:59], v[162:165], v[186:189], v[56:59]
	v_mfma_f32_16x16x32_bf16 v[44:47], v[146:149], v[194:197], v[44:47]
	v_mfma_f32_16x16x32_bf16 v[40:43], v[162:165], v[194:197], v[40:43]
	v_mfma_f32_16x16x32_bf16 v[28:31], v[146:149], v[214:217], v[28:31]
	v_mfma_f32_16x16x32_bf16 v[24:27], v[162:165], v[214:217], v[24:27]
	v_mfma_f32_16x16x32_bf16 v[12:15], v[146:149], v[222:225], v[12:15]
	v_mfma_f32_16x16x32_bf16 v[8:11], v[162:165], v[222:225], v[8:11]
	v_mfma_f32_16x16x32_bf16 v[52:55], v[166:169], v[182:185], v[52:55]
	v_mfma_f32_16x16x32_bf16 v[48:51], v[174:177], v[182:185], v[48:51]
	v_mfma_f32_16x16x32_bf16 v[36:39], v[166:169], v[190:193], v[36:39]
	v_mfma_f32_16x16x32_bf16 v[32:35], v[174:177], v[190:193], v[32:35]
	v_mfma_f32_16x16x32_bf16 v[20:23], v[166:169], v[210:213], v[20:23]
	v_mfma_f32_16x16x32_bf16 v[16:19], v[174:177], v[210:213], v[16:19]
	v_mfma_f32_16x16x32_bf16 v[4:7], v[166:169], v[218:221], v[4:7]
	v_mfma_f32_16x16x32_bf16 v[0:3], v[174:177], v[218:221], v[0:3]
	v_mfma_f32_16x16x32_bf16 v[52:55], v[170:173], v[186:189], v[52:55]
	v_mfma_f32_16x16x32_bf16 v[48:51], v[178:181], v[186:189], v[48:51]
	v_mfma_f32_16x16x32_bf16 v[36:39], v[170:173], v[194:197], v[36:39]
	v_mfma_f32_16x16x32_bf16 v[32:35], v[178:181], v[194:197], v[32:35]
	v_mfma_f32_16x16x32_bf16 v[20:23], v[170:173], v[214:217], v[20:23]
	v_mfma_f32_16x16x32_bf16 v[16:19], v[178:181], v[214:217], v[16:19]
	v_mfma_f32_16x16x32_bf16 v[4:7], v[170:173], v[222:225], v[4:7]
	v_mfma_f32_16x16x32_bf16 v[0:3], v[178:181], v[222:225], v[0:3]
	s_barrier
	s_add_i32 s62, 0, 0x18000
	v_add_u32_e32 v132, s62, v151
	s_add_i32 s63, 0, 0x1c000
	ds_read_b128 v[142:145], v132
	ds_read_b128 v[146:149], v132 offset:1024
	ds_read_b128 v[158:161], v132 offset:2048
	ds_read_b128 v[162:165], v132 offset:3072
	v_add_u32_e32 v132, s63, v151
	ds_read_b128 v[166:169], v132
	ds_read_b128 v[170:173], v132 offset:1024
	ds_read_b128 v[174:177], v132 offset:2048
	ds_read_b128 v[178:181], v132 offset:3072
	s_add_u32 s46, s46, 0x80000
	s_addc_u32 s47, s47, 0
	s_mov_b32 m0, s49
	v_lshl_add_u64 v[232:233], s[46:47], 0, v[128:129]
	ds_read_b128 v[182:185], v157 offset:32768
	ds_read_b128 v[186:189], v157 offset:33792
	ds_read_b128 v[190:193], v157 offset:34816
	ds_read_b128 v[194:197], v157 offset:35840
	ds_read_b128 v[210:213], v157 offset:36864
	ds_read_b128 v[214:217], v157 offset:37888
	ds_read_b128 v[218:221], v157 offset:38912
	ds_read_b128 v[222:225], v157 offset:39936
	global_load_lds_dwordx4 v[232:233], off
	v_lshl_add_u64 v[232:233], s[46:47], 0, v[130:131]
	s_mov_b32 m0, s50
	s_nop 0
	global_load_lds_dwordx4 v[232:233], off
	s_waitcnt vmcnt(8)
	s_waitcnt lgkmcnt(0)
	s_barrier
	s_waitcnt lgkmcnt(0)
	v_mfma_f32_16x16x32_bf16 v[124:127], v[142:145], v[182:185], v[124:127]
	v_mfma_f32_16x16x32_bf16 v[120:123], v[158:161], v[182:185], v[120:123]
	v_mfma_f32_16x16x32_bf16 v[108:111], v[142:145], v[190:193], v[108:111]
	v_mfma_f32_16x16x32_bf16 v[104:107], v[158:161], v[190:193], v[104:107]
	v_mfma_f32_16x16x32_bf16 v[92:95], v[142:145], v[210:213], v[92:95]
	v_mfma_f32_16x16x32_bf16 v[88:91], v[158:161], v[210:213], v[88:91]
	v_mfma_f32_16x16x32_bf16 v[76:79], v[142:145], v[218:221], v[76:79]
	v_mfma_f32_16x16x32_bf16 v[72:75], v[158:161], v[218:221], v[72:75]
	v_mfma_f32_16x16x32_bf16 v[124:127], v[146:149], v[186:189], v[124:127]
	v_mfma_f32_16x16x32_bf16 v[120:123], v[162:165], v[186:189], v[120:123]
	v_mfma_f32_16x16x32_bf16 v[108:111], v[146:149], v[194:197], v[108:111]
	v_mfma_f32_16x16x32_bf16 v[104:107], v[162:165], v[194:197], v[104:107]
	v_mfma_f32_16x16x32_bf16 v[92:95], v[146:149], v[214:217], v[92:95]
	v_mfma_f32_16x16x32_bf16 v[88:91], v[162:165], v[214:217], v[88:91]
	v_mfma_f32_16x16x32_bf16 v[76:79], v[146:149], v[222:225], v[76:79]
	v_mfma_f32_16x16x32_bf16 v[72:75], v[162:165], v[222:225], v[72:75]
	v_mfma_f32_16x16x32_bf16 v[116:119], v[166:169], v[182:185], v[116:119]
	v_mfma_f32_16x16x32_bf16 v[112:115], v[174:177], v[182:185], v[112:115]
	v_mfma_f32_16x16x32_bf16 v[100:103], v[166:169], v[190:193], v[100:103]
	v_mfma_f32_16x16x32_bf16 v[96:99], v[174:177], v[190:193], v[96:99]
	v_mfma_f32_16x16x32_bf16 v[84:87], v[166:169], v[210:213], v[84:87]
	v_mfma_f32_16x16x32_bf16 v[80:83], v[174:177], v[210:213], v[80:83]
	v_mfma_f32_16x16x32_bf16 v[68:71], v[166:169], v[218:221], v[68:71]
	v_mfma_f32_16x16x32_bf16 v[64:67], v[174:177], v[218:221], v[64:67]
	v_mfma_f32_16x16x32_bf16 v[116:119], v[170:173], v[186:189], v[116:119]
	v_mfma_f32_16x16x32_bf16 v[112:115], v[178:181], v[186:189], v[112:115]
	v_mfma_f32_16x16x32_bf16 v[100:103], v[170:173], v[194:197], v[100:103]
	v_mfma_f32_16x16x32_bf16 v[96:99], v[178:181], v[194:197], v[96:99]
	v_mfma_f32_16x16x32_bf16 v[84:87], v[170:173], v[214:217], v[84:87]
	v_mfma_f32_16x16x32_bf16 v[80:83], v[178:181], v[214:217], v[80:83]
	v_mfma_f32_16x16x32_bf16 v[68:71], v[170:173], v[222:225], v[68:71]
	v_mfma_f32_16x16x32_bf16 v[64:67], v[178:181], v[222:225], v[64:67]
	s_barrier
	s_add_i32 s46, s62, s4
	v_lshl_add_u64 v[198:199], v[198:199], 0, s[24:25]
	s_mov_b32 m0, s46
	ds_read_b128 v[182:185], v157 offset:49152
	ds_read_b128 v[186:189], v157 offset:50176
	ds_read_b128 v[190:193], v157 offset:51200
	ds_read_b128 v[194:197], v157 offset:52224
	ds_read_b128 v[210:213], v157 offset:53248
	ds_read_b128 v[214:217], v157 offset:54272
	ds_read_b128 v[218:221], v157 offset:55296
	ds_read_b128 v[222:225], v157 offset:56320
	global_load_lds_dwordx4 v[198:199], off
	s_add_i32 m0, s46, 0x2000
	s_add_u32 s44, s44, 0x80080
	v_lshl_add_u64 v[198:199], v[226:227], 0, s[24:25]
	s_addc_u32 s45, s45, 0
	s_add_i32 s46, s63, s4
	global_load_lds_dwordx4 v[198:199], off
	v_lshl_add_u64 v[198:199], s[44:45], 0, v[128:129]
	s_mov_b32 m0, s46
	s_nop 0
	global_load_lds_dwordx4 v[198:199], off
	v_lshl_add_u64 v[198:199], s[44:45], 0, v[130:131]
	s_add_i32 m0, s46, 0x2000
	s_nop 0
	global_load_lds_dwordx4 v[198:199], off
	v_lshl_add_u64 v[198:199], v[228:229], 0, s[24:25]
	s_mov_b32 m0, s54
	s_nop 0
	global_load_lds_dwordx4 v[198:199], off
	v_lshl_add_u64 v[198:199], v[230:231], 0, s[24:25]
	s_mov_b32 m0, s55
	s_nop 0
	global_load_lds_dwordx4 v[198:199], off
	s_waitcnt vmcnt(8)
	s_waitcnt lgkmcnt(0)
	s_barrier
	s_waitcnt lgkmcnt(0)
	v_mfma_f32_16x16x32_bf16 v[60:63], v[142:145], v[182:185], v[60:63]
	v_mfma_f32_16x16x32_bf16 v[56:59], v[158:161], v[182:185], v[56:59]
	v_mfma_f32_16x16x32_bf16 v[44:47], v[142:145], v[190:193], v[44:47]
	v_mfma_f32_16x16x32_bf16 v[40:43], v[158:161], v[190:193], v[40:43]
	v_mfma_f32_16x16x32_bf16 v[28:31], v[142:145], v[210:213], v[28:31]
	v_mfma_f32_16x16x32_bf16 v[24:27], v[158:161], v[210:213], v[24:27]
	v_mfma_f32_16x16x32_bf16 v[12:15], v[142:145], v[218:221], v[12:15]
	v_mfma_f32_16x16x32_bf16 v[8:11], v[158:161], v[218:221], v[8:11]
	v_mfma_f32_16x16x32_bf16 v[60:63], v[146:149], v[186:189], v[60:63]
	v_mfma_f32_16x16x32_bf16 v[56:59], v[162:165], v[186:189], v[56:59]
	v_mfma_f32_16x16x32_bf16 v[44:47], v[146:149], v[194:197], v[44:47]
	v_mfma_f32_16x16x32_bf16 v[40:43], v[162:165], v[194:197], v[40:43]
	v_mfma_f32_16x16x32_bf16 v[28:31], v[146:149], v[214:217], v[28:31]
	v_mfma_f32_16x16x32_bf16 v[24:27], v[162:165], v[214:217], v[24:27]
	v_mfma_f32_16x16x32_bf16 v[12:15], v[146:149], v[222:225], v[12:15]
	v_mfma_f32_16x16x32_bf16 v[8:11], v[162:165], v[222:225], v[8:11]
	v_mfma_f32_16x16x32_bf16 v[52:55], v[166:169], v[182:185], v[52:55]
	v_mfma_f32_16x16x32_bf16 v[48:51], v[174:177], v[182:185], v[48:51]
	v_mfma_f32_16x16x32_bf16 v[36:39], v[166:169], v[190:193], v[36:39]
	v_mfma_f32_16x16x32_bf16 v[32:35], v[174:177], v[190:193], v[32:35]
	v_mfma_f32_16x16x32_bf16 v[20:23], v[166:169], v[210:213], v[20:23]
	v_mfma_f32_16x16x32_bf16 v[16:19], v[174:177], v[210:213], v[16:19]
	v_mfma_f32_16x16x32_bf16 v[4:7], v[166:169], v[218:221], v[4:7]
	v_mfma_f32_16x16x32_bf16 v[0:3], v[174:177], v[218:221], v[0:3]
	v_mfma_f32_16x16x32_bf16 v[52:55], v[170:173], v[186:189], v[52:55]
	v_mfma_f32_16x16x32_bf16 v[48:51], v[178:181], v[186:189], v[48:51]
	v_mfma_f32_16x16x32_bf16 v[36:39], v[170:173], v[194:197], v[36:39]
	v_mfma_f32_16x16x32_bf16 v[32:35], v[178:181], v[194:197], v[32:35]
	v_mfma_f32_16x16x32_bf16 v[20:23], v[170:173], v[214:217], v[20:23]
	v_mfma_f32_16x16x32_bf16 v[16:19], v[178:181], v[214:217], v[16:19]
	v_mfma_f32_16x16x32_bf16 v[4:7], v[170:173], v[222:225], v[4:7]
	v_mfma_f32_16x16x32_bf16 v[0:3], v[178:181], v[222:225], v[0:3]
	s_barrier
	s_add_i32 s61, s61, 2
	s_add_u32 s59, s59, 0x100
	s_addc_u32 s60, s60, 0
	s_add_u32 s42, s42, 0x100
	s_addc_u32 s43, s43, 0
	s_cmp_gt_u32 s61, 29
	s_cbranch_scc0 .LBB0_299
	s_setprio 0
	s_and_b64 vcc, exec, s[26:27]
	s_cbranch_vccz .LBB0_302
	s_barrier

.LBB0_408:
	s_ashr_i32 s31, s30, 31
	s_lshl_b64 s[10:11], s[30:31], 19
	s_add_u32 s34, s0, s10
	s_addc_u32 s35, s1, s11
	s_and_b64 s[10:11], s[8:9], exec
	s_cselect_b32 s13, s35, s43
	s_cselect_b32 s31, s34, s42
	s_ashr_i32 s29, s28, 31
	s_lshl_b64 s[10:11], s[28:29], 19
	s_add_u32 s36, s4, s10
	s_addc_u32 s37, s5, s11
	s_and_b64 s[10:11], s[8:9], exec
	s_cselect_b32 s29, s37, s41
	s_cselect_b32 s39, s36, s40
	s_add_u32 s64, s40, 0x100
	s_addc_u32 s65, s41, 0
	s_add_u32 s10, s42, 0x40080
	v_mov_b32_e32 v0, 0
	s_addc_u32 s11, s43, 0
	s_mov_b32 s66, -2
	v_mov_b32_e32 v1, v0
	v_mov_b32_e32 v2, v0
	v_mov_b32_e32 v3, v0
	v_mov_b32_e32 v4, v0
	v_mov_b32_e32 v5, v0
	v_mov_b32_e32 v6, v0
	v_mov_b32_e32 v7, v0
	v_mov_b32_e32 v16, v0
	v_mov_b32_e32 v17, v0
	v_mov_b32_e32 v18, v0
	v_mov_b32_e32 v19, v0
	v_mov_b32_e32 v20, v0
	v_mov_b32_e32 v21, v0
	v_mov_b32_e32 v22, v0
	v_mov_b32_e32 v23, v0
	v_mov_b32_e32 v32, v0
	v_mov_b32_e32 v33, v0
	v_mov_b32_e32 v34, v0
	v_mov_b32_e32 v35, v0
	v_mov_b32_e32 v36, v0
	v_mov_b32_e32 v37, v0
	v_mov_b32_e32 v38, v0
	v_mov_b32_e32 v39, v0
	v_mov_b32_e32 v48, v0
	v_mov_b32_e32 v49, v0
	v_mov_b32_e32 v50, v0
	v_mov_b32_e32 v51, v0
	v_mov_b32_e32 v52, v0
	v_mov_b32_e32 v53, v0
	v_mov_b32_e32 v54, v0
	v_mov_b32_e32 v55, v0
	v_mov_b32_e32 v8, v0
	v_mov_b32_e32 v9, v0
	v_mov_b32_e32 v10, v0
	v_mov_b32_e32 v11, v0
	v_mov_b32_e32 v12, v0
	v_mov_b32_e32 v13, v0
	v_mov_b32_e32 v14, v0
	v_mov_b32_e32 v15, v0
	v_mov_b32_e32 v24, v0
	v_mov_b32_e32 v25, v0
	v_mov_b32_e32 v26, v0
	v_mov_b32_e32 v27, v0
	v_mov_b32_e32 v28, v0
	v_mov_b32_e32 v29, v0
	v_mov_b32_e32 v30, v0
	v_mov_b32_e32 v31, v0
	v_mov_b32_e32 v40, v0
	v_mov_b32_e32 v41, v0
	v_mov_b32_e32 v42, v0
	v_mov_b32_e32 v43, v0
	v_mov_b32_e32 v44, v0
	v_mov_b32_e32 v45, v0
	v_mov_b32_e32 v46, v0
	v_mov_b32_e32 v47, v0
	v_mov_b32_e32 v56, v0
	v_mov_b32_e32 v57, v0
	v_mov_b32_e32 v58, v0
	v_mov_b32_e32 v59, v0
	v_mov_b32_e32 v60, v0
	v_mov_b32_e32 v61, v0
	v_mov_b32_e32 v62, v0
	v_mov_b32_e32 v63, v0
	v_mov_b32_e32 v64, v0
	v_mov_b32_e32 v65, v0
	v_mov_b32_e32 v66, v0
	v_mov_b32_e32 v67, v0
	v_mov_b32_e32 v68, v0
	v_mov_b32_e32 v69, v0
	v_mov_b32_e32 v70, v0
	v_mov_b32_e32 v71, v0
	v_mov_b32_e32 v80, v0
	v_mov_b32_e32 v81, v0
	v_mov_b32_e32 v82, v0
	v_mov_b32_e32 v83, v0
	v_mov_b32_e32 v84, v0
	v_mov_b32_e32 v85, v0
	v_mov_b32_e32 v86, v0
	v_mov_b32_e32 v87, v0
	v_mov_b32_e32 v96, v0
	v_mov_b32_e32 v97, v0
	v_mov_b32_e32 v98, v0
	v_mov_b32_e32 v99, v0
	v_mov_b32_e32 v100, v0
	v_mov_b32_e32 v101, v0
	v_mov_b32_e32 v102, v0
	v_mov_b32_e32 v103, v0
	v_mov_b32_e32 v112, v0
	v_mov_b32_e32 v113, v0
	v_mov_b32_e32 v114, v0
	v_mov_b32_e32 v115, v0
	v_mov_b32_e32 v116, v0
	v_mov_b32_e32 v117, v0
	v_mov_b32_e32 v118, v0
	v_mov_b32_e32 v119, v0
	v_mov_b32_e32 v72, v0
	v_mov_b32_e32 v73, v0
	v_mov_b32_e32 v74, v0
	v_mov_b32_e32 v75, v0
	v_mov_b32_e32 v76, v0
	v_mov_b32_e32 v77, v0
	v_mov_b32_e32 v78, v0
	v_mov_b32_e32 v79, v0
	v_mov_b32_e32 v88, v0
	v_mov_b32_e32 v89, v0
	v_mov_b32_e32 v90, v0
	v_mov_b32_e32 v91, v0
	v_mov_b32_e32 v92, v0
	v_mov_b32_e32 v93, v0
	v_mov_b32_e32 v94, v0
	v_mov_b32_e32 v95, v0
	v_mov_b32_e32 v104, v0
	v_mov_b32_e32 v105, v0
	v_mov_b32_e32 v106, v0
	v_mov_b32_e32 v107, v0
	v_mov_b32_e32 v108, v0
	v_mov_b32_e32 v109, v0
	v_mov_b32_e32 v110, v0
	v_mov_b32_e32 v111, v0
	v_mov_b32_e32 v120, v0
	v_mov_b32_e32 v121, v0
	v_mov_b32_e32 v122, v0
	v_mov_b32_e32 v123, v0
	v_mov_b32_e32 v124, v0
	v_mov_b32_e32 v125, v0
	v_mov_b32_e32 v126, v0
	v_mov_b32_e32 v127, v0
	v_readfirstlane_b32 s99, v201
	s_cmp_lt_u32 s99, 0x100
	s_cbranch_scc1 .Lprio_skip2
	s_setprio 1
.Lprio_skip2:
.LBB0_409:
	ds_read_b128 v[148:151], v156
	ds_read_b128 v[160:163], v156 offset:1024
	ds_read_b128 v[164:167], v156 offset:2048
	ds_read_b128 v[168:171], v156 offset:3072
	ds_read_b128 v[172:175], v157
	ds_read_b128 v[176:179], v157 offset:1024
	ds_read_b128 v[180:183], v157 offset:2048
	ds_read_b128 v[184:187], v157 offset:3072
	s_add_u32 s40, s10, 0xfffc0080
	s_addc_u32 s41, s11, -1
	s_cmp_eq_u32 s66, 12
	s_cselect_b32 s43, s13, s41
	s_cselect_b32 s42, s31, s40
	s_cselect_b32 s41, s29, s65
	s_cselect_b32 s40, s39, s64
	v_lshl_add_u64 v[152:153], s[10:11], 0, v[142:143]
	s_add_i32 m0, s45, 0xc000
	ds_read_b128 v[188:191], v158
	ds_read_b128 v[192:195], v158 offset:1024
	ds_read_b128 v[196:199], v158 offset:2048
	ds_read_b128 v[210:213], v158 offset:3072
	ds_read_b128 v[214:217], v158 offset:4096
	ds_read_b128 v[218:221], v158 offset:5120
	ds_read_b128 v[222:225], v158 offset:6144
	ds_read_b128 v[226:229], v158 offset:7168
	global_load_lds_dwordx4 v[152:153], off
	v_lshl_add_u64 v[152:153], s[10:11], 0, v[140:141]
	s_add_i32 m0, s45, 0xe000
	s_nop 0
	global_load_lds_dwordx4 v[152:153], off
	s_waitcnt vmcnt(8)
	s_waitcnt lgkmcnt(0)
	s_barrier
	s_waitcnt lgkmcnt(0)
	v_mfma_f32_16x16x32_bf16 v[124:127], v[148:151], v[188:191], v[124:127]
	v_mfma_f32_16x16x32_bf16 v[120:123], v[164:167], v[188:191], v[120:123]
	v_mfma_f32_16x16x32_bf16 v[108:111], v[148:151], v[196:199], v[108:111]
	v_mfma_f32_16x16x32_bf16 v[104:107], v[164:167], v[196:199], v[104:107]
	v_mfma_f32_16x16x32_bf16 v[92:95], v[148:151], v[214:217], v[92:95]
	v_mfma_f32_16x16x32_bf16 v[88:91], v[164:167], v[214:217], v[88:91]
	v_mfma_f32_16x16x32_bf16 v[76:79], v[148:151], v[222:225], v[76:79]
	v_mfma_f32_16x16x32_bf16 v[72:75], v[164:167], v[222:225], v[72:75]
	v_mfma_f32_16x16x32_bf16 v[124:127], v[160:163], v[192:195], v[124:127]
	v_mfma_f32_16x16x32_bf16 v[120:123], v[168:171], v[192:195], v[120:123]
	v_mfma_f32_16x16x32_bf16 v[108:111], v[160:163], v[210:213], v[108:111]
	v_mfma_f32_16x16x32_bf16 v[104:107], v[168:171], v[210:213], v[104:107]
	v_mfma_f32_16x16x32_bf16 v[92:95], v[160:163], v[218:221], v[92:95]
	v_mfma_f32_16x16x32_bf16 v[88:91], v[168:171], v[218:221], v[88:91]
	v_mfma_f32_16x16x32_bf16 v[76:79], v[160:163], v[226:229], v[76:79]
	v_mfma_f32_16x16x32_bf16 v[72:75], v[168:171], v[226:229], v[72:75]
	v_mfma_f32_16x16x32_bf16 v[116:119], v[172:175], v[188:191], v[116:119]
	v_mfma_f32_16x16x32_bf16 v[112:115], v[180:183], v[188:191], v[112:115]
	v_mfma_f32_16x16x32_bf16 v[100:103], v[172:175], v[196:199], v[100:103]
	v_mfma_f32_16x16x32_bf16 v[96:99], v[180:183], v[196:199], v[96:99]
	v_mfma_f32_16x16x32_bf16 v[84:87], v[172:175], v[214:217], v[84:87]
	v_mfma_f32_16x16x32_bf16 v[80:83], v[180:183], v[214:217], v[80:83]
	v_mfma_f32_16x16x32_bf16 v[68:71], v[172:175], v[222:225], v[68:71]
	v_mfma_f32_16x16x32_bf16 v[64:67], v[180:183], v[222:225], v[64:67]
	v_mfma_f32_16x16x32_bf16 v[116:119], v[176:179], v[192:195], v[116:119]
	v_mfma_f32_16x16x32_bf16 v[112:115], v[184:187], v[192:195], v[112:115]
	v_mfma_f32_16x16x32_bf16 v[100:103], v[176:179], v[210:213], v[100:103]
	v_mfma_f32_16x16x32_bf16 v[96:99], v[184:187], v[210:213], v[96:99]
	v_mfma_f32_16x16x32_bf16 v[84:87], v[176:179], v[218:221], v[84:87]
	v_mfma_f32_16x16x32_bf16 v[80:83], v[184:187], v[218:221], v[80:83]
	v_mfma_f32_16x16x32_bf16 v[68:71], v[176:179], v[226:229], v[68:71]
	v_mfma_f32_16x16x32_bf16 v[64:67], v[184:187], v[226:229], v[64:67]
	s_barrier
	s_add_i32 s67, s59, s44
	v_lshl_add_u64 v[152:153], s[40:41], 0, v[130:131]
	s_mov_b32 m0, s67
	ds_read_b128 v[188:191], v158 offset:16384
	ds_read_b128 v[192:195], v158 offset:17408
	ds_read_b128 v[196:199], v158 offset:18432
	ds_read_b128 v[210:213], v158 offset:19456
	ds_read_b128 v[214:217], v158 offset:20480
	ds_read_b128 v[218:221], v158 offset:21504
	ds_read_b128 v[222:225], v158 offset:22528
	ds_read_b128 v[226:229], v158 offset:23552
	global_load_lds_dwordx4 v[152:153], off
	s_add_i32 m0, s67, 0x2000
	s_add_u32 s68, s40, 0x40000
	v_lshl_add_u64 v[230:231], s[40:41], 0, v[134:135]
	s_addc_u32 s69, s41, 0
	s_add_i32 s67, s60, s44
	global_load_lds_dwordx4 v[230:231], off
	v_lshl_add_u64 v[232:233], s[68:69], 0, v[130:131]
	s_mov_b32 m0, s67
	v_lshl_add_u64 v[234:235], s[42:43], 0, v[132:133]
	global_load_lds_dwordx4 v[232:233], off
	v_lshl_add_u64 v[232:233], s[68:69], 0, v[134:135]
	s_add_i32 m0, s67, 0x2000
	s_nop 0
	global_load_lds_dwordx4 v[232:233], off
	v_lshl_add_u64 v[232:233], s[42:43], 0, v[128:129]
	s_mov_b32 m0, s45
	s_nop 0
	global_load_lds_dwordx4 v[232:233], off
	s_mov_b32 m0, s46
	s_nop 0
	global_load_lds_dwordx4 v[234:235], off
	s_waitcnt vmcnt(8)
	s_waitcnt lgkmcnt(0)
	s_barrier
	s_waitcnt lgkmcnt(0)
	v_mfma_f32_16x16x32_bf16 v[60:63], v[148:151], v[188:191], v[60:63]
	v_mfma_f32_16x16x32_bf16 v[56:59], v[164:167], v[188:191], v[56:59]
	v_mfma_f32_16x16x32_bf16 v[44:47], v[148:151], v[196:199], v[44:47]
	v_mfma_f32_16x16x32_bf16 v[40:43], v[164:167], v[196:199], v[40:43]
	v_mfma_f32_16x16x32_bf16 v[28:31], v[148:151], v[214:217], v[28:31]
	v_mfma_f32_16x16x32_bf16 v[24:27], v[164:167], v[214:217], v[24:27]
	v_mfma_f32_16x16x32_bf16 v[12:15], v[148:151], v[222:225], v[12:15]
	v_mfma_f32_16x16x32_bf16 v[8:11], v[164:167], v[222:225], v[8:11]
	v_mfma_f32_16x16x32_bf16 v[60:63], v[160:163], v[192:195], v[60:63]
	v_mfma_f32_16x16x32_bf16 v[56:59], v[168:171], v[192:195], v[56:59]
	v_mfma_f32_16x16x32_bf16 v[44:47], v[160:163], v[210:213], v[44:47]
	v_mfma_f32_16x16x32_bf16 v[40:43], v[168:171], v[210:213], v[40:43]
	v_mfma_f32_16x16x32_bf16 v[28:31], v[160:163], v[218:221], v[28:31]
	v_mfma_f32_16x16x32_bf16 v[24:27], v[168:171], v[218:221], v[24:27]
	v_mfma_f32_16x16x32_bf16 v[12:15], v[160:163], v[226:229], v[12:15]
	v_mfma_f32_16x16x32_bf16 v[8:11], v[168:171], v[226:229], v[8:11]
	v_mfma_f32_16x16x32_bf16 v[52:55], v[172:175], v[188:191], v[52:55]
	v_mfma_f32_16x16x32_bf16 v[48:51], v[180:183], v[188:191], v[48:51]
	v_mfma_f32_16x16x32_bf16 v[36:39], v[172:175], v[196:199], v[36:39]
	v_mfma_f32_16x16x32_bf16 v[32:35], v[180:183], v[196:199], v[32:35]
	v_mfma_f32_16x16x32_bf16 v[20:23], v[172:175], v[214:217], v[20:23]
	v_mfma_f32_16x16x32_bf16 v[16:19], v[180:183], v[214:217], v[16:19]
	v_mfma_f32_16x16x32_bf16 v[4:7], v[172:175], v[222:225], v[4:7]
	v_mfma_f32_16x16x32_bf16 v[0:3], v[180:183], v[222:225], v[0:3]
	v_mfma_f32_16x16x32_bf16 v[52:55], v[176:179], v[192:195], v[52:55]
	v_mfma_f32_16x16x32_bf16 v[48:51], v[184:187], v[192:195], v[48:51]
	v_mfma_f32_16x16x32_bf16 v[36:39], v[176:179], v[210:213], v[36:39]
	v_mfma_f32_16x16x32_bf16 v[32:35], v[184:187], v[210:213], v[32:35]
	v_mfma_f32_16x16x32_bf16 v[20:23], v[176:179], v[218:221], v[20:23]
	v_mfma_f32_16x16x32_bf16 v[16:19], v[184:187], v[218:221], v[16:19]
	v_mfma_f32_16x16x32_bf16 v[4:7], v[176:179], v[226:229], v[4:7]
	v_mfma_f32_16x16x32_bf16 v[0:3], v[184:187], v[226:229], v[0:3]
	s_barrier
	s_add_i32 s67, 0, 0x18000
	v_add_u32_e32 v136, s67, v154
	s_add_i32 s68, 0, 0x1c000
	ds_read_b128 v[148:151], v136
	ds_read_b128 v[160:163], v136 offset:1024
	ds_read_b128 v[164:167], v136 offset:2048
	ds_read_b128 v[168:171], v136 offset:3072
	v_add_u32_e32 v136, s68, v154
	ds_read_b128 v[172:175], v136
	ds_read_b128 v[176:179], v136 offset:1024
	ds_read_b128 v[180:183], v136 offset:2048
	ds_read_b128 v[184:187], v136 offset:3072
	s_add_u32 s42, s42, 0x40000
	s_addc_u32 s43, s43, 0
	s_mov_b32 m0, s47
	v_lshl_add_u64 v[236:237], s[42:43], 0, v[128:129]
	ds_read_b128 v[188:191], v158 offset:32768
	ds_read_b128 v[192:195], v158 offset:33792
	ds_read_b128 v[196:199], v158 offset:34816
	ds_read_b128 v[210:213], v158 offset:35840
	ds_read_b128 v[214:217], v158 offset:36864
	ds_read_b128 v[218:221], v158 offset:37888
	ds_read_b128 v[222:225], v158 offset:38912
	ds_read_b128 v[226:229], v158 offset:39936
	global_load_lds_dwordx4 v[236:237], off
	v_lshl_add_u64 v[236:237], s[42:43], 0, v[132:133]
	s_mov_b32 m0, s48
	s_nop 0
	global_load_lds_dwordx4 v[236:237], off
	s_waitcnt vmcnt(8)
	s_waitcnt lgkmcnt(0)
	s_barrier
	s_waitcnt lgkmcnt(0)
	v_mfma_f32_16x16x32_bf16 v[124:127], v[148:151], v[188:191], v[124:127]
	v_mfma_f32_16x16x32_bf16 v[120:123], v[164:167], v[188:191], v[120:123]
	v_mfma_f32_16x16x32_bf16 v[108:111], v[148:151], v[196:199], v[108:111]
	v_mfma_f32_16x16x32_bf16 v[104:107], v[164:167], v[196:199], v[104:107]
	v_mfma_f32_16x16x32_bf16 v[92:95], v[148:151], v[214:217], v[92:95]
	v_mfma_f32_16x16x32_bf16 v[88:91], v[164:167], v[214:217], v[88:91]
	v_mfma_f32_16x16x32_bf16 v[76:79], v[148:151], v[222:225], v[76:79]
	v_mfma_f32_16x16x32_bf16 v[72:75], v[164:167], v[222:225], v[72:75]
	v_mfma_f32_16x16x32_bf16 v[124:127], v[160:163], v[192:195], v[124:127]
	v_mfma_f32_16x16x32_bf16 v[120:123], v[168:171], v[192:195], v[120:123]
	v_mfma_f32_16x16x32_bf16 v[108:111], v[160:163], v[210:213], v[108:111]
	v_mfma_f32_16x16x32_bf16 v[104:107], v[168:171], v[210:213], v[104:107]
	v_mfma_f32_16x16x32_bf16 v[92:95], v[160:163], v[218:221], v[92:95]
	v_mfma_f32_16x16x32_bf16 v[88:91], v[168:171], v[218:221], v[88:91]
	v_mfma_f32_16x16x32_bf16 v[76:79], v[160:163], v[226:229], v[76:79]
	v_mfma_f32_16x16x32_bf16 v[72:75], v[168:171], v[226:229], v[72:75]
	v_mfma_f32_16x16x32_bf16 v[116:119], v[172:175], v[188:191], v[116:119]
	v_mfma_f32_16x16x32_bf16 v[112:115], v[180:183], v[188:191], v[112:115]
	v_mfma_f32_16x16x32_bf16 v[100:103], v[172:175], v[196:199], v[100:103]
	v_mfma_f32_16x16x32_bf16 v[96:99], v[180:183], v[196:199], v[96:99]
	v_mfma_f32_16x16x32_bf16 v[84:87], v[172:175], v[214:217], v[84:87]
	v_mfma_f32_16x16x32_bf16 v[80:83], v[180:183], v[214:217], v[80:83]
	v_mfma_f32_16x16x32_bf16 v[68:71], v[172:175], v[222:225], v[68:71]
	v_mfma_f32_16x16x32_bf16 v[64:67], v[180:183], v[222:225], v[64:67]
	v_mfma_f32_16x16x32_bf16 v[116:119], v[176:179], v[192:195], v[116:119]
	v_mfma_f32_16x16x32_bf16 v[112:115], v[184:187], v[192:195], v[112:115]
	v_mfma_f32_16x16x32_bf16 v[100:103], v[176:179], v[210:213], v[100:103]
	v_mfma_f32_16x16x32_bf16 v[96:99], v[184:187], v[210:213], v[96:99]
	v_mfma_f32_16x16x32_bf16 v[84:87], v[176:179], v[218:221], v[84:87]
	v_mfma_f32_16x16x32_bf16 v[80:83], v[184:187], v[218:221], v[80:83]
	v_mfma_f32_16x16x32_bf16 v[68:71], v[176:179], v[226:229], v[68:71]
	v_mfma_f32_16x16x32_bf16 v[64:67], v[184:187], v[226:229], v[64:67]
	s_barrier
	s_add_i32 s42, s67, s44
	v_lshl_add_u64 v[152:153], v[152:153], 0, s[18:19]
	s_mov_b32 m0, s42
	ds_read_b128 v[188:191], v158 offset:49152
	ds_read_b128 v[192:195], v158 offset:50176
	ds_read_b128 v[196:199], v158 offset:51200
	ds_read_b128 v[210:213], v158 offset:52224
	ds_read_b128 v[214:217], v158 offset:53248
	ds_read_b128 v[218:221], v158 offset:54272
	ds_read_b128 v[222:225], v158 offset:55296
	ds_read_b128 v[226:229], v158 offset:56320
	global_load_lds_dwordx4 v[152:153], off
	s_add_i32 m0, s42, 0x2000
	s_add_u32 s40, s40, 0x40080
	v_lshl_add_u64 v[152:153], v[230:231], 0, s[18:19]
	s_addc_u32 s41, s41, 0
	s_add_i32 s42, s68, s44
	global_load_lds_dwordx4 v[152:153], off
	v_lshl_add_u64 v[152:153], s[40:41], 0, v[130:131]
	s_mov_b32 m0, s42
	s_nop 0
	global_load_lds_dwordx4 v[152:153], off
	v_lshl_add_u64 v[152:153], s[40:41], 0, v[134:135]
	s_add_i32 m0, s42, 0x2000
	s_nop 0
	global_load_lds_dwordx4 v[152:153], off
	v_lshl_add_u64 v[152:153], v[232:233], 0, s[18:19]
	s_mov_b32 m0, s56
	s_nop 0
	global_load_lds_dwordx4 v[152:153], off
	v_lshl_add_u64 v[152:153], v[234:235], 0, s[18:19]
	s_mov_b32 m0, s57
	s_nop 0
	global_load_lds_dwordx4 v[152:153], off
	s_waitcnt vmcnt(8)
	s_waitcnt lgkmcnt(0)
	s_barrier
	s_waitcnt lgkmcnt(0)
	v_mfma_f32_16x16x32_bf16 v[60:63], v[148:151], v[188:191], v[60:63]
	v_mfma_f32_16x16x32_bf16 v[56:59], v[164:167], v[188:191], v[56:59]
	v_mfma_f32_16x16x32_bf16 v[44:47], v[148:151], v[196:199], v[44:47]
	v_mfma_f32_16x16x32_bf16 v[40:43], v[164:167], v[196:199], v[40:43]
	v_mfma_f32_16x16x32_bf16 v[28:31], v[148:151], v[214:217], v[28:31]
	v_mfma_f32_16x16x32_bf16 v[24:27], v[164:167], v[214:217], v[24:27]
	v_mfma_f32_16x16x32_bf16 v[12:15], v[148:151], v[222:225], v[12:15]
	v_mfma_f32_16x16x32_bf16 v[8:11], v[164:167], v[222:225], v[8:11]
	v_mfma_f32_16x16x32_bf16 v[60:63], v[160:163], v[192:195], v[60:63]
	v_mfma_f32_16x16x32_bf16 v[56:59], v[168:171], v[192:195], v[56:59]
	v_mfma_f32_16x16x32_bf16 v[44:47], v[160:163], v[210:213], v[44:47]
	v_mfma_f32_16x16x32_bf16 v[40:43], v[168:171], v[210:213], v[40:43]
	v_mfma_f32_16x16x32_bf16 v[28:31], v[160:163], v[218:221], v[28:31]
	v_mfma_f32_16x16x32_bf16 v[24:27], v[168:171], v[218:221], v[24:27]
	v_mfma_f32_16x16x32_bf16 v[12:15], v[160:163], v[226:229], v[12:15]
	v_mfma_f32_16x16x32_bf16 v[8:11], v[168:171], v[226:229], v[8:11]
	v_mfma_f32_16x16x32_bf16 v[52:55], v[172:175], v[188:191], v[52:55]
	v_mfma_f32_16x16x32_bf16 v[48:51], v[180:183], v[188:191], v[48:51]
	v_mfma_f32_16x16x32_bf16 v[36:39], v[172:175], v[196:199], v[36:39]
	v_mfma_f32_16x16x32_bf16 v[32:35], v[180:183], v[196:199], v[32:35]
	v_mfma_f32_16x16x32_bf16 v[20:23], v[172:175], v[214:217], v[20:23]
	v_mfma_f32_16x16x32_bf16 v[16:19], v[180:183], v[214:217], v[16:19]
	v_mfma_f32_16x16x32_bf16 v[4:7], v[172:175], v[222:225], v[4:7]
	v_mfma_f32_16x16x32_bf16 v[0:3], v[180:183], v[222:225], v[0:3]
	v_mfma_f32_16x16x32_bf16 v[52:55], v[176:179], v[192:195], v[52:55]
	v_mfma_f32_16x16x32_bf16 v[48:51], v[184:187], v[192:195], v[48:51]
	v_mfma_f32_16x16x32_bf16 v[36:39], v[176:179], v[210:213], v[36:39]
	v_mfma_f32_16x16x32_bf16 v[32:35], v[184:187], v[210:213], v[32:35]
	v_mfma_f32_16x16x32_bf16 v[20:23], v[176:179], v[218:221], v[20:23]
	v_mfma_f32_16x16x32_bf16 v[16:19], v[184:187], v[218:221], v[16:19]
	v_mfma_f32_16x16x32_bf16 v[4:7], v[176:179], v[226:229], v[4:7]
	v_mfma_f32_16x16x32_bf16 v[0:3], v[184:187], v[226:229], v[0:3]
	s_barrier
	s_add_i32 s66, s66, 2
	s_add_u32 s64, s64, 0x100
	s_addc_u32 s65, s65, 0
	s_add_u32 s10, s10, 0x100
	s_addc_u32 s11, s11, 0
	s_cmp_gt_u32 s66, 13
	s_cbranch_scc0 .LBB0_409
	s_setprio 0
	s_and_b64 vcc, exec, s[20:21]
	s_cbranch_vccz .LBB0_412
	s_barrier

.LBB0_653:
	s_ashr_i32 s27, s26, 31
	s_lshl_b64 s[28:29], s[26:27], 20
	s_add_u32 s28, s5, s28
	s_addc_u32 s29, s42, s29
	s_and_b64 s[30:31], s[8:9], exec
	s_cselect_b32 s27, s29, s37
	s_cselect_b32 s59, s28, s36
	s_ashr_i32 s25, s24, 31
	s_lshl_b64 s[30:31], s[24:25], 20
	s_add_u32 s30, s43, s30
	s_addc_u32 s31, s46, s31
	s_and_b64 s[38:39], s[8:9], exec
	s_cselect_b32 s25, s31, s35
	s_cselect_b32 s60, s30, s34
	s_add_u32 s61, s34, 0x100
	s_addc_u32 s62, s35, 0
	s_add_u32 s34, s36, 0x80080
	v_mov_b32_e32 v32, 0
	s_addc_u32 s35, s37, 0
	s_mov_b32 s63, -2
	v_mov_b32_e32 v33, v32
	v_mov_b32_e32 v34, v32
	v_mov_b32_e32 v35, v32
	v_mov_b32_e32 v36, v32
	v_mov_b32_e32 v37, v32
	v_mov_b32_e32 v38, v32
	v_mov_b32_e32 v39, v32
	v_mov_b32_e32 v56, v32
	v_mov_b32_e32 v57, v32
	v_mov_b32_e32 v58, v32
	v_mov_b32_e32 v59, v32
	v_mov_b32_e32 v60, v32
	v_mov_b32_e32 v61, v32
	v_mov_b32_e32 v62, v32
	v_mov_b32_e32 v63, v32
	v_mov_b32_e32 v80, v32
	v_mov_b32_e32 v81, v32
	v_mov_b32_e32 v82, v32
	v_mov_b32_e32 v83, v32
	v_mov_b32_e32 v84, v32
	v_mov_b32_e32 v85, v32
	v_mov_b32_e32 v86, v32
	v_mov_b32_e32 v87, v32
	v_mov_b32_e32 v88, v32
	v_mov_b32_e32 v89, v32
	v_mov_b32_e32 v90, v32
	v_mov_b32_e32 v91, v32
	v_mov_b32_e32 v92, v32
	v_mov_b32_e32 v93, v32
	v_mov_b32_e32 v94, v32
	v_mov_b32_e32 v95, v32
	v_mov_b32_e32 v0, v32
	v_mov_b32_e32 v1, v32
	v_mov_b32_e32 v2, v32
	v_mov_b32_e32 v3, v32
	v_mov_b32_e32 v4, v32
	v_mov_b32_e32 v5, v32
	v_mov_b32_e32 v6, v32
	v_mov_b32_e32 v7, v32
	v_mov_b32_e32 v8, v32
	v_mov_b32_e32 v9, v32
	v_mov_b32_e32 v10, v32
	v_mov_b32_e32 v11, v32
	v_mov_b32_e32 v12, v32
	v_mov_b32_e32 v13, v32
	v_mov_b32_e32 v14, v32
	v_mov_b32_e32 v15, v32
	v_mov_b32_e32 v16, v32
	v_mov_b32_e32 v17, v32
	v_mov_b32_e32 v18, v32
	v_mov_b32_e32 v19, v32
	v_mov_b32_e32 v20, v32
	v_mov_b32_e32 v21, v32
	v_mov_b32_e32 v22, v32
	v_mov_b32_e32 v23, v32
	v_mov_b32_e32 v24, v32
	v_mov_b32_e32 v25, v32
	v_mov_b32_e32 v26, v32
	v_mov_b32_e32 v27, v32
	v_mov_b32_e32 v28, v32
	v_mov_b32_e32 v29, v32
	v_mov_b32_e32 v30, v32
	v_mov_b32_e32 v31, v32
	v_mov_b32_e32 v96, v32
	v_mov_b32_e32 v97, v32
	v_mov_b32_e32 v98, v32
	v_mov_b32_e32 v99, v32
	v_mov_b32_e32 v100, v32
	v_mov_b32_e32 v101, v32
	v_mov_b32_e32 v102, v32
	v_mov_b32_e32 v103, v32
	v_mov_b32_e32 v104, v32
	v_mov_b32_e32 v105, v32
	v_mov_b32_e32 v106, v32
	v_mov_b32_e32 v107, v32
	v_mov_b32_e32 v108, v32
	v_mov_b32_e32 v109, v32
	v_mov_b32_e32 v110, v32
	v_mov_b32_e32 v111, v32
	v_mov_b32_e32 v112, v32
	v_mov_b32_e32 v113, v32
	v_mov_b32_e32 v114, v32
	v_mov_b32_e32 v115, v32
	v_mov_b32_e32 v116, v32
	v_mov_b32_e32 v117, v32
	v_mov_b32_e32 v118, v32
	v_mov_b32_e32 v119, v32
	v_mov_b32_e32 v120, v32
	v_mov_b32_e32 v121, v32
	v_mov_b32_e32 v122, v32
	v_mov_b32_e32 v123, v32
	v_mov_b32_e32 v124, v32
	v_mov_b32_e32 v125, v32
	v_mov_b32_e32 v126, v32
	v_mov_b32_e32 v127, v32
	v_mov_b32_e32 v40, v32
	v_mov_b32_e32 v41, v32
	v_mov_b32_e32 v42, v32
	v_mov_b32_e32 v43, v32
	v_mov_b32_e32 v44, v32
	v_mov_b32_e32 v45, v32
	v_mov_b32_e32 v46, v32
	v_mov_b32_e32 v47, v32
	v_mov_b32_e32 v48, v32
	v_mov_b32_e32 v49, v32
	v_mov_b32_e32 v50, v32
	v_mov_b32_e32 v51, v32
	v_mov_b32_e32 v52, v32
	v_mov_b32_e32 v53, v32
	v_mov_b32_e32 v54, v32
	v_mov_b32_e32 v55, v32
	v_mov_b32_e32 v64, v32
	v_mov_b32_e32 v65, v32
	v_mov_b32_e32 v66, v32
	v_mov_b32_e32 v67, v32
	v_mov_b32_e32 v68, v32
	v_mov_b32_e32 v69, v32
	v_mov_b32_e32 v70, v32
	v_mov_b32_e32 v71, v32
	v_mov_b32_e32 v72, v32
	v_mov_b32_e32 v73, v32
	v_mov_b32_e32 v74, v32
	v_mov_b32_e32 v75, v32
	v_mov_b32_e32 v76, v32
	v_mov_b32_e32 v77, v32
	v_mov_b32_e32 v78, v32
	v_mov_b32_e32 v79, v32
	v_readfirstlane_b32 s99, v201
	s_cmp_lt_u32 s99, 0x100
	s_cbranch_scc1 .Lprio_skip3
	s_setprio 1
.Lprio_skip3:
.LBB0_654:
	ds_read_b128 v[144:147], v151
	ds_read_b128 v[154:157], v151 offset:1024
	ds_read_b128 v[158:161], v151 offset:2048
	ds_read_b128 v[162:165], v151 offset:3072
	ds_read_b128 v[166:169], v152
	ds_read_b128 v[170:173], v152 offset:1024
	ds_read_b128 v[174:177], v152 offset:2048
	ds_read_b128 v[178:181], v152 offset:3072
	s_add_u32 s36, s34, 0xfff80080
	s_addc_u32 s37, s35, -1
	s_cmp_eq_u32 s63, 28
	s_cselect_b32 s39, s27, s37
	s_cselect_b32 s38, s59, s36
	s_cselect_b32 s37, s25, s62
	s_cselect_b32 s36, s60, s61
	v_lshl_add_u64 v[198:199], s[34:35], 0, v[138:139]
	s_add_i32 m0, s21, 0xc000
	ds_read_b128 v[182:185], v153
	ds_read_b128 v[186:189], v153 offset:1024
	ds_read_b128 v[190:193], v153 offset:2048
	ds_read_b128 v[194:197], v153 offset:3072
	ds_read_b128 v[210:213], v153 offset:4096
	ds_read_b128 v[214:217], v153 offset:5120
	ds_read_b128 v[218:221], v153 offset:6144
	ds_read_b128 v[222:225], v153 offset:7168
	global_load_lds_dwordx4 v[198:199], off
	v_lshl_add_u64 v[198:199], s[34:35], 0, v[136:137]
	s_add_i32 m0, s21, 0xe000
	s_nop 0
	global_load_lds_dwordx4 v[198:199], off
	s_waitcnt vmcnt(8)
	s_waitcnt lgkmcnt(0)
	s_barrier
	s_waitcnt lgkmcnt(0)
	v_mfma_f32_16x16x32_bf16 v[76:79], v[144:147], v[182:185], v[76:79]
	v_mfma_f32_16x16x32_bf16 v[72:75], v[158:161], v[182:185], v[72:75]
	v_mfma_f32_16x16x32_bf16 v[68:71], v[144:147], v[190:193], v[68:71]
	v_mfma_f32_16x16x32_bf16 v[64:67], v[158:161], v[190:193], v[64:67]
	v_mfma_f32_16x16x32_bf16 v[52:55], v[144:147], v[210:213], v[52:55]
	v_mfma_f32_16x16x32_bf16 v[48:51], v[158:161], v[210:213], v[48:51]
	v_mfma_f32_16x16x32_bf16 v[44:47], v[144:147], v[218:221], v[44:47]
	v_mfma_f32_16x16x32_bf16 v[40:43], v[158:161], v[218:221], v[40:43]
	v_mfma_f32_16x16x32_bf16 v[76:79], v[154:157], v[186:189], v[76:79]
	v_mfma_f32_16x16x32_bf16 v[72:75], v[162:165], v[186:189], v[72:75]
	v_mfma_f32_16x16x32_bf16 v[68:71], v[154:157], v[194:197], v[68:71]
	v_mfma_f32_16x16x32_bf16 v[64:67], v[162:165], v[194:197], v[64:67]
	v_mfma_f32_16x16x32_bf16 v[52:55], v[154:157], v[214:217], v[52:55]
	v_mfma_f32_16x16x32_bf16 v[48:51], v[162:165], v[214:217], v[48:51]
	v_mfma_f32_16x16x32_bf16 v[44:47], v[154:157], v[222:225], v[44:47]
	v_mfma_f32_16x16x32_bf16 v[40:43], v[162:165], v[222:225], v[40:43]
	v_mfma_f32_16x16x32_bf16 v[124:127], v[166:169], v[182:185], v[124:127]
	v_mfma_f32_16x16x32_bf16 v[120:123], v[174:177], v[182:185], v[120:123]
	v_mfma_f32_16x16x32_bf16 v[116:119], v[166:169], v[190:193], v[116:119]
	v_mfma_f32_16x16x32_bf16 v[112:115], v[174:177], v[190:193], v[112:115]
	v_mfma_f32_16x16x32_bf16 v[108:111], v[166:169], v[210:213], v[108:111]
	v_mfma_f32_16x16x32_bf16 v[104:107], v[174:177], v[210:213], v[104:107]
	v_mfma_f32_16x16x32_bf16 v[100:103], v[166:169], v[218:221], v[100:103]
	v_mfma_f32_16x16x32_bf16 v[96:99], v[174:177], v[218:221], v[96:99]
	v_mfma_f32_16x16x32_bf16 v[124:127], v[170:173], v[186:189], v[124:127]
	v_mfma_f32_16x16x32_bf16 v[120:123], v[178:181], v[186:189], v[120:123]
	v_mfma_f32_16x16x32_bf16 v[116:119], v[170:173], v[194:197], v[116:119]
	v_mfma_f32_16x16x32_bf16 v[112:115], v[178:181], v[194:197], v[112:115]
	v_mfma_f32_16x16x32_bf16 v[108:111], v[170:173], v[214:217], v[108:111]
	v_mfma_f32_16x16x32_bf16 v[104:107], v[178:181], v[214:217], v[104:107]
	v_mfma_f32_16x16x32_bf16 v[100:103], v[170:173], v[222:225], v[100:103]
	v_mfma_f32_16x16x32_bf16 v[96:99], v[178:181], v[222:225], v[96:99]
	s_barrier
	s_add_i32 s64, s56, s47
	v_lshl_add_u64 v[198:199], s[36:37], 0, v[130:131]
	s_mov_b32 m0, s64
	ds_read_b128 v[182:185], v153 offset:16384
	ds_read_b128 v[186:189], v153 offset:17408
	ds_read_b128 v[190:193], v153 offset:18432
	ds_read_b128 v[194:197], v153 offset:19456
	ds_read_b128 v[210:213], v153 offset:20480
	ds_read_b128 v[214:217], v153 offset:21504
	ds_read_b128 v[218:221], v153 offset:22528
	ds_read_b128 v[222:225], v153 offset:23552
	global_load_lds_dwordx4 v[198:199], off
	s_add_i32 m0, s64, 0x2000
	s_add_u32 s64, s36, 0x80000
	v_lshl_add_u64 v[226:227], s[36:37], 0, v[134:135]
	s_addc_u32 s65, s37, 0
	s_add_i32 s66, s57, s47
	global_load_lds_dwordx4 v[226:227], off
	v_lshl_add_u64 v[228:229], s[64:65], 0, v[130:131]
	s_mov_b32 m0, s66
	v_lshl_add_u64 v[230:231], s[38:39], 0, v[132:133]
	global_load_lds_dwordx4 v[228:229], off
	v_lshl_add_u64 v[228:229], s[64:65], 0, v[134:135]
	s_add_i32 m0, s66, 0x2000
	s_nop 0
	global_load_lds_dwordx4 v[228:229], off
	v_lshl_add_u64 v[228:229], s[38:39], 0, v[128:129]
	s_mov_b32 m0, s21
	s_nop 0
	global_load_lds_dwordx4 v[228:229], off
	s_mov_b32 m0, s48
	s_nop 0
	global_load_lds_dwordx4 v[230:231], off
	s_waitcnt vmcnt(8)
	s_waitcnt lgkmcnt(0)
	s_barrier
	s_waitcnt lgkmcnt(0)
	v_mfma_f32_16x16x32_bf16 v[28:31], v[144:147], v[182:185], v[28:31]
	v_mfma_f32_16x16x32_bf16 v[24:27], v[158:161], v[182:185], v[24:27]
	v_mfma_f32_16x16x32_bf16 v[20:23], v[144:147], v[190:193], v[20:23]
	v_mfma_f32_16x16x32_bf16 v[16:19], v[158:161], v[190:193], v[16:19]
	v_mfma_f32_16x16x32_bf16 v[12:15], v[144:147], v[210:213], v[12:15]
	v_mfma_f32_16x16x32_bf16 v[8:11], v[158:161], v[210:213], v[8:11]
	v_mfma_f32_16x16x32_bf16 v[4:7], v[144:147], v[218:221], v[4:7]
	v_mfma_f32_16x16x32_bf16 v[0:3], v[158:161], v[218:221], v[0:3]
	v_mfma_f32_16x16x32_bf16 v[28:31], v[154:157], v[186:189], v[28:31]
	v_mfma_f32_16x16x32_bf16 v[24:27], v[162:165], v[186:189], v[24:27]
	v_mfma_f32_16x16x32_bf16 v[20:23], v[154:157], v[194:197], v[20:23]
	v_mfma_f32_16x16x32_bf16 v[16:19], v[162:165], v[194:197], v[16:19]
	v_mfma_f32_16x16x32_bf16 v[12:15], v[154:157], v[214:217], v[12:15]
	v_mfma_f32_16x16x32_bf16 v[8:11], v[162:165], v[214:217], v[8:11]
	v_mfma_f32_16x16x32_bf16 v[4:7], v[154:157], v[222:225], v[4:7]
	v_mfma_f32_16x16x32_bf16 v[0:3], v[162:165], v[222:225], v[0:3]
	v_mfma_f32_16x16x32_bf16 v[92:95], v[166:169], v[182:185], v[92:95]
	v_mfma_f32_16x16x32_bf16 v[88:91], v[174:177], v[182:185], v[88:91]
	v_mfma_f32_16x16x32_bf16 v[84:87], v[166:169], v[190:193], v[84:87]
	v_mfma_f32_16x16x32_bf16 v[80:83], v[174:177], v[190:193], v[80:83]
	v_mfma_f32_16x16x32_bf16 v[60:63], v[166:169], v[210:213], v[60:63]
	v_mfma_f32_16x16x32_bf16 v[56:59], v[174:177], v[210:213], v[56:59]
	v_mfma_f32_16x16x32_bf16 v[36:39], v[166:169], v[218:221], v[36:39]
	v_mfma_f32_16x16x32_bf16 v[32:35], v[174:177], v[218:221], v[32:35]
	v_mfma_f32_16x16x32_bf16 v[92:95], v[170:173], v[186:189], v[92:95]
	v_mfma_f32_16x16x32_bf16 v[88:91], v[178:181], v[186:189], v[88:91]
	v_mfma_f32_16x16x32_bf16 v[84:87], v[170:173], v[194:197], v[84:87]
	v_mfma_f32_16x16x32_bf16 v[80:83], v[178:181], v[194:197], v[80:83]
	v_mfma_f32_16x16x32_bf16 v[60:63], v[170:173], v[214:217], v[60:63]
	v_mfma_f32_16x16x32_bf16 v[56:59], v[178:181], v[214:217], v[56:59]
	v_mfma_f32_16x16x32_bf16 v[36:39], v[170:173], v[222:225], v[36:39]
	v_mfma_f32_16x16x32_bf16 v[32:35], v[178:181], v[222:225], v[32:35]
	s_barrier
	s_add_i32 s64, 0, 0x18000
	s_add_i32 s65, 0, 0x1c000
	v_add_u32_e32 v162, s64, v149
	v_add_u32_e32 v178, s65, v149
	ds_read_b128 v[144:147], v162
	ds_read_b128 v[154:157], v162 offset:1024
	ds_read_b128 v[158:161], v162 offset:2048
	ds_read_b128 v[162:165], v162 offset:3072
	ds_read_b128 v[166:169], v178
	ds_read_b128 v[170:173], v178 offset:1024
	ds_read_b128 v[174:177], v178 offset:2048
	ds_read_b128 v[178:181], v178 offset:3072
	s_add_u32 s38, s38, 0x80000
	s_addc_u32 s39, s39, 0
	s_mov_b32 m0, s49
	v_lshl_add_u64 v[232:233], s[38:39], 0, v[128:129]
	ds_read_b128 v[182:185], v153 offset:32768
	ds_read_b128 v[186:189], v153 offset:33792
	ds_read_b128 v[190:193], v153 offset:34816
	ds_read_b128 v[194:197], v153 offset:35840
	ds_read_b128 v[210:213], v153 offset:36864
	ds_read_b128 v[214:217], v153 offset:37888
	ds_read_b128 v[218:221], v153 offset:38912
	ds_read_b128 v[222:225], v153 offset:39936
	global_load_lds_dwordx4 v[232:233], off
	v_lshl_add_u64 v[232:233], s[38:39], 0, v[132:133]
	s_mov_b32 m0, s50
	s_nop 0
	global_load_lds_dwordx4 v[232:233], off
	s_waitcnt vmcnt(8)
	s_waitcnt lgkmcnt(0)
	s_barrier
	s_waitcnt lgkmcnt(0)
	v_mfma_f32_16x16x32_bf16 v[76:79], v[144:147], v[182:185], v[76:79]
	v_mfma_f32_16x16x32_bf16 v[72:75], v[158:161], v[182:185], v[72:75]
	v_mfma_f32_16x16x32_bf16 v[68:71], v[144:147], v[190:193], v[68:71]
	v_mfma_f32_16x16x32_bf16 v[64:67], v[158:161], v[190:193], v[64:67]
	v_mfma_f32_16x16x32_bf16 v[52:55], v[144:147], v[210:213], v[52:55]
	v_mfma_f32_16x16x32_bf16 v[48:51], v[158:161], v[210:213], v[48:51]
	v_mfma_f32_16x16x32_bf16 v[44:47], v[144:147], v[218:221], v[44:47]
	v_mfma_f32_16x16x32_bf16 v[40:43], v[158:161], v[218:221], v[40:43]
	v_mfma_f32_16x16x32_bf16 v[76:79], v[154:157], v[186:189], v[76:79]
	v_mfma_f32_16x16x32_bf16 v[72:75], v[162:165], v[186:189], v[72:75]
	v_mfma_f32_16x16x32_bf16 v[68:71], v[154:157], v[194:197], v[68:71]
	v_mfma_f32_16x16x32_bf16 v[64:67], v[162:165], v[194:197], v[64:67]
	v_mfma_f32_16x16x32_bf16 v[52:55], v[154:157], v[214:217], v[52:55]
	v_mfma_f32_16x16x32_bf16 v[48:51], v[162:165], v[214:217], v[48:51]
	v_mfma_f32_16x16x32_bf16 v[44:47], v[154:157], v[222:225], v[44:47]
	v_mfma_f32_16x16x32_bf16 v[40:43], v[162:165], v[222:225], v[40:43]
	v_mfma_f32_16x16x32_bf16 v[124:127], v[166:169], v[182:185], v[124:127]
	v_mfma_f32_16x16x32_bf16 v[120:123], v[174:177], v[182:185], v[120:123]
	v_mfma_f32_16x16x32_bf16 v[116:119], v[166:169], v[190:193], v[116:119]
	v_mfma_f32_16x16x32_bf16 v[112:115], v[174:177], v[190:193], v[112:115]
	v_mfma_f32_16x16x32_bf16 v[108:111], v[166:169], v[210:213], v[108:111]
	v_mfma_f32_16x16x32_bf16 v[104:107], v[174:177], v[210:213], v[104:107]
	v_mfma_f32_16x16x32_bf16 v[100:103], v[166:169], v[218:221], v[100:103]
	v_mfma_f32_16x16x32_bf16 v[96:99], v[174:177], v[218:221], v[96:99]
	v_mfma_f32_16x16x32_bf16 v[124:127], v[170:173], v[186:189], v[124:127]
	v_mfma_f32_16x16x32_bf16 v[120:123], v[178:181], v[186:189], v[120:123]
	v_mfma_f32_16x16x32_bf16 v[116:119], v[170:173], v[194:197], v[116:119]
	v_mfma_f32_16x16x32_bf16 v[112:115], v[178:181], v[194:197], v[112:115]
	v_mfma_f32_16x16x32_bf16 v[108:111], v[170:173], v[214:217], v[108:111]
	v_mfma_f32_16x16x32_bf16 v[104:107], v[178:181], v[214:217], v[104:107]
	v_mfma_f32_16x16x32_bf16 v[100:103], v[170:173], v[222:225], v[100:103]
	v_mfma_f32_16x16x32_bf16 v[96:99], v[178:181], v[222:225], v[96:99]
	s_barrier
	s_add_i32 s38, s64, s47
	v_lshl_add_u64 v[198:199], v[198:199], 0, s[18:19]
	s_mov_b32 m0, s38
	ds_read_b128 v[182:185], v153 offset:49152
	ds_read_b128 v[186:189], v153 offset:50176
	ds_read_b128 v[190:193], v153 offset:51200
	ds_read_b128 v[194:197], v153 offset:52224
	ds_read_b128 v[210:213], v153 offset:53248
	ds_read_b128 v[214:217], v153 offset:54272
	ds_read_b128 v[218:221], v153 offset:55296
	ds_read_b128 v[222:225], v153 offset:56320
	global_load_lds_dwordx4 v[198:199], off
	s_add_i32 m0, s38, 0x2000
	s_add_u32 s36, s36, 0x80080
	v_lshl_add_u64 v[198:199], v[226:227], 0, s[18:19]
	s_addc_u32 s37, s37, 0
	s_add_i32 s38, s65, s47
	global_load_lds_dwordx4 v[198:199], off
	v_lshl_add_u64 v[198:199], s[36:37], 0, v[130:131]
	s_mov_b32 m0, s38
	s_nop 0
	global_load_lds_dwordx4 v[198:199], off
	v_lshl_add_u64 v[198:199], s[36:37], 0, v[134:135]
	s_add_i32 m0, s38, 0x2000
	s_nop 0
	global_load_lds_dwordx4 v[198:199], off
	v_lshl_add_u64 v[198:199], v[228:229], 0, s[18:19]
	s_mov_b32 m0, s54
	s_nop 0
	global_load_lds_dwordx4 v[198:199], off
	v_lshl_add_u64 v[198:199], v[230:231], 0, s[18:19]
	s_mov_b32 m0, s55
	s_nop 0
	global_load_lds_dwordx4 v[198:199], off
	s_waitcnt vmcnt(8)
	s_waitcnt lgkmcnt(0)
	s_barrier
	s_waitcnt lgkmcnt(0)
	v_mfma_f32_16x16x32_bf16 v[28:31], v[144:147], v[182:185], v[28:31]
	v_mfma_f32_16x16x32_bf16 v[24:27], v[158:161], v[182:185], v[24:27]
	v_mfma_f32_16x16x32_bf16 v[20:23], v[144:147], v[190:193], v[20:23]
	v_mfma_f32_16x16x32_bf16 v[16:19], v[158:161], v[190:193], v[16:19]
	v_mfma_f32_16x16x32_bf16 v[12:15], v[144:147], v[210:213], v[12:15]
	v_mfma_f32_16x16x32_bf16 v[8:11], v[158:161], v[210:213], v[8:11]
	v_mfma_f32_16x16x32_bf16 v[4:7], v[144:147], v[218:221], v[4:7]
	v_mfma_f32_16x16x32_bf16 v[0:3], v[158:161], v[218:221], v[0:3]
	v_mfma_f32_16x16x32_bf16 v[28:31], v[154:157], v[186:189], v[28:31]
	v_mfma_f32_16x16x32_bf16 v[24:27], v[162:165], v[186:189], v[24:27]
	v_mfma_f32_16x16x32_bf16 v[20:23], v[154:157], v[194:197], v[20:23]
	v_mfma_f32_16x16x32_bf16 v[16:19], v[162:165], v[194:197], v[16:19]
	v_mfma_f32_16x16x32_bf16 v[12:15], v[154:157], v[214:217], v[12:15]
	v_mfma_f32_16x16x32_bf16 v[8:11], v[162:165], v[214:217], v[8:11]
	v_mfma_f32_16x16x32_bf16 v[4:7], v[154:157], v[222:225], v[4:7]
	v_mfma_f32_16x16x32_bf16 v[0:3], v[162:165], v[222:225], v[0:3]
	v_mfma_f32_16x16x32_bf16 v[92:95], v[166:169], v[182:185], v[92:95]
	v_mfma_f32_16x16x32_bf16 v[88:91], v[174:177], v[182:185], v[88:91]
	v_mfma_f32_16x16x32_bf16 v[84:87], v[166:169], v[190:193], v[84:87]
	v_mfma_f32_16x16x32_bf16 v[80:83], v[174:177], v[190:193], v[80:83]
	v_mfma_f32_16x16x32_bf16 v[60:63], v[166:169], v[210:213], v[60:63]
	v_mfma_f32_16x16x32_bf16 v[56:59], v[174:177], v[210:213], v[56:59]
	v_mfma_f32_16x16x32_bf16 v[36:39], v[166:169], v[218:221], v[36:39]
	v_mfma_f32_16x16x32_bf16 v[32:35], v[174:177], v[218:221], v[32:35]
	v_mfma_f32_16x16x32_bf16 v[92:95], v[170:173], v[186:189], v[92:95]
	v_mfma_f32_16x16x32_bf16 v[88:91], v[178:181], v[186:189], v[88:91]
	v_mfma_f32_16x16x32_bf16 v[84:87], v[170:173], v[194:197], v[84:87]
	v_mfma_f32_16x16x32_bf16 v[80:83], v[178:181], v[194:197], v[80:83]
	v_mfma_f32_16x16x32_bf16 v[60:63], v[170:173], v[214:217], v[60:63]
	v_mfma_f32_16x16x32_bf16 v[56:59], v[178:181], v[214:217], v[56:59]
	v_mfma_f32_16x16x32_bf16 v[36:39], v[170:173], v[222:225], v[36:39]
	v_mfma_f32_16x16x32_bf16 v[32:35], v[178:181], v[222:225], v[32:35]
	s_barrier
	s_add_i32 s63, s63, 2
	s_add_u32 s61, s61, 0x100
	s_addc_u32 s62, s62, 0
	s_add_u32 s34, s34, 0x100
	s_addc_u32 s35, s35, 0
	s_cmp_gt_u32 s63, 29
	s_cbranch_scc0 .LBB0_654
	s_setprio 0
	s_and_b64 vcc, exec, s[22:23]
	s_cbranch_vccnz .LBB0_659
	s_cmp_lg_u32 s58, 8
	s_mov_b64 s[34:35], -1
	s_cbranch_scc1 .LBB0_660

.LBB0_675:
	s_ashr_i32 s29, s28, 31
	s_lshl_b64 s[30:31], s[28:29], 20
	s_add_u32 s30, s5, s30
	s_addc_u32 s31, s42, s31
	s_and_b64 s[34:35], s[6:7], exec
	s_cselect_b32 s29, s31, s39
	s_cselect_b32 s61, s30, s38
	s_ashr_i32 s27, s26, 31
	s_lshl_b64 s[34:35], s[26:27], 20
	s_add_u32 s34, s45, s34
	s_addc_u32 s35, s46, s35
	s_and_b64 s[40:41], s[6:7], exec
	s_cselect_b32 s27, s35, s37
	s_cselect_b32 s62, s34, s36
	s_add_u32 s63, s36, 0x100
	s_addc_u32 s64, s37, 0
	s_add_u32 s36, s38, 0x80080
	v_mov_b32_e32 v16, 0
	s_addc_u32 s37, s39, 0
	s_mov_b32 s65, -2
	v_mov_b32_e32 v17, v16
	v_mov_b32_e32 v18, v16
	v_mov_b32_e32 v19, v16
	v_mov_b32_e32 v20, v16
	v_mov_b32_e32 v21, v16
	v_mov_b32_e32 v22, v16
	v_mov_b32_e32 v23, v16
	v_mov_b32_e32 v44, v16
	v_mov_b32_e32 v45, v16
	v_mov_b32_e32 v46, v16
	v_mov_b32_e32 v47, v16
	v_mov_b32_e32 v48, v16
	v_mov_b32_e32 v49, v16
	v_mov_b32_e32 v50, v16
	v_mov_b32_e32 v51, v16
	v_mov_b32_e32 v56, v16
	v_mov_b32_e32 v57, v16
	v_mov_b32_e32 v58, v16
	v_mov_b32_e32 v59, v16
	v_mov_b32_e32 v60, v16
	v_mov_b32_e32 v61, v16
	v_mov_b32_e32 v62, v16
	v_mov_b32_e32 v63, v16
	v_mov_b32_e32 v68, v16
	v_mov_b32_e32 v69, v16
	v_mov_b32_e32 v70, v16
	v_mov_b32_e32 v71, v16
	v_mov_b32_e32 v72, v16
	v_mov_b32_e32 v73, v16
	v_mov_b32_e32 v74, v16
	v_mov_b32_e32 v75, v16
	v_mov_b32_e32 v32, v16
	v_mov_b32_e32 v33, v16
	v_mov_b32_e32 v34, v16
	v_mov_b32_e32 v35, v16
	v_mov_b32_e32 v0, v16
	v_mov_b32_e32 v1, v16
	v_mov_b32_e32 v2, v16
	v_mov_b32_e32 v3, v16
	v_mov_b32_e32 v52, v16
	v_mov_b32_e32 v53, v16
	v_mov_b32_e32 v54, v16
	v_mov_b32_e32 v55, v16
	v_mov_b32_e32 v4, v16
	v_mov_b32_e32 v5, v16
	v_mov_b32_e32 v6, v16
	v_mov_b32_e32 v7, v16
	v_mov_b32_e32 v64, v16
	v_mov_b32_e32 v65, v16
	v_mov_b32_e32 v66, v16
	v_mov_b32_e32 v67, v16
	v_mov_b32_e32 v8, v16
	v_mov_b32_e32 v9, v16
	v_mov_b32_e32 v10, v16
	v_mov_b32_e32 v11, v16
	v_mov_b32_e32 v76, v16
	v_mov_b32_e32 v77, v16
	v_mov_b32_e32 v78, v16
	v_mov_b32_e32 v79, v16
	v_mov_b32_e32 v12, v16
	v_mov_b32_e32 v13, v16
	v_mov_b32_e32 v14, v16
	v_mov_b32_e32 v15, v16
	v_mov_b32_e32 v80, v16
	v_mov_b32_e32 v81, v16
	v_mov_b32_e32 v82, v16
	v_mov_b32_e32 v83, v16
	v_mov_b32_e32 v84, v16
	v_mov_b32_e32 v85, v16
	v_mov_b32_e32 v86, v16
	v_mov_b32_e32 v87, v16
	v_mov_b32_e32 v92, v16
	v_mov_b32_e32 v93, v16
	v_mov_b32_e32 v94, v16
	v_mov_b32_e32 v95, v16
	v_mov_b32_e32 v96, v16
	v_mov_b32_e32 v97, v16
	v_mov_b32_e32 v98, v16
	v_mov_b32_e32 v99, v16
	v_mov_b32_e32 v104, v16
	v_mov_b32_e32 v105, v16
	v_mov_b32_e32 v106, v16
	v_mov_b32_e32 v107, v16
	v_mov_b32_e32 v108, v16
	v_mov_b32_e32 v109, v16
	v_mov_b32_e32 v110, v16
	v_mov_b32_e32 v111, v16
	v_mov_b32_e32 v116, v16
	v_mov_b32_e32 v117, v16
	v_mov_b32_e32 v118, v16
	v_mov_b32_e32 v119, v16
	v_mov_b32_e32 v120, v16
	v_mov_b32_e32 v121, v16
	v_mov_b32_e32 v122, v16
	v_mov_b32_e32 v123, v16
	v_mov_b32_e32 v88, v16
	v_mov_b32_e32 v89, v16
	v_mov_b32_e32 v90, v16
	v_mov_b32_e32 v91, v16
	v_mov_b32_e32 v24, v16
	v_mov_b32_e32 v25, v16
	v_mov_b32_e32 v26, v16
	v_mov_b32_e32 v27, v16
	v_mov_b32_e32 v100, v16
	v_mov_b32_e32 v101, v16
	v_mov_b32_e32 v102, v16
	v_mov_b32_e32 v103, v16
	v_mov_b32_e32 v28, v16
	v_mov_b32_e32 v29, v16
	v_mov_b32_e32 v30, v16
	v_mov_b32_e32 v31, v16
	v_mov_b32_e32 v112, v16
	v_mov_b32_e32 v113, v16
	v_mov_b32_e32 v114, v16
	v_mov_b32_e32 v115, v16
	v_mov_b32_e32 v36, v16
	v_mov_b32_e32 v37, v16
	v_mov_b32_e32 v38, v16
	v_mov_b32_e32 v39, v16
	v_mov_b32_e32 v124, v16
	v_mov_b32_e32 v125, v16
	v_mov_b32_e32 v126, v16
	v_mov_b32_e32 v127, v16
	v_mov_b32_e32 v40, v16
	v_mov_b32_e32 v41, v16
	v_mov_b32_e32 v42, v16
	v_mov_b32_e32 v43, v16
	v_readfirstlane_b32 s99, v201
	s_cmp_lt_u32 s99, 0x100
	s_cbranch_scc1 .Lprio_skip4
	s_setprio 1
.Lprio_skip4:
.LBB0_676:
	ds_read_b128 v[142:145], v151
	ds_read_b128 v[154:157], v151 offset:1024
	ds_read_b128 v[158:161], v151 offset:2048
	ds_read_b128 v[162:165], v151 offset:3072
	ds_read_b128 v[166:169], v152
	ds_read_b128 v[170:173], v152 offset:1024
	ds_read_b128 v[174:177], v152 offset:2048
	ds_read_b128 v[178:181], v152 offset:3072
	s_add_u32 s38, s36, 0xfff80080
	s_addc_u32 s39, s37, -1
	s_cmp_eq_u32 s65, 28
	s_cselect_b32 s41, s29, s39
	s_cselect_b32 s40, s61, s38
	s_cselect_b32 s39, s27, s64
	s_cselect_b32 s38, s62, s63
	v_lshl_add_u64 v[146:147], s[36:37], 0, v[136:137]
	s_add_i32 m0, s21, 0xc000
	ds_read_b128 v[182:185], v153
	ds_read_b128 v[186:189], v153 offset:1024
	ds_read_b128 v[190:193], v153 offset:2048
	ds_read_b128 v[194:197], v153 offset:3072
	ds_read_b128 v[210:213], v153 offset:4096
	ds_read_b128 v[214:217], v153 offset:5120
	ds_read_b128 v[218:221], v153 offset:6144
	ds_read_b128 v[222:225], v153 offset:7168
	global_load_lds_dwordx4 v[146:147], off
	v_lshl_add_u64 v[146:147], s[36:37], 0, v[134:135]
	s_add_i32 m0, s21, 0xe000
	s_nop 0
	global_load_lds_dwordx4 v[146:147], off
	s_waitcnt vmcnt(8)
	s_waitcnt lgkmcnt(0)
	s_barrier
	s_waitcnt lgkmcnt(0)
	v_mfma_f32_16x16x32_bf16 v[40:43], v[182:185], v[142:145], v[40:43]
	v_mfma_f32_16x16x32_bf16 v[124:127], v[182:185], v[158:161], v[124:127]
	v_mfma_f32_16x16x32_bf16 v[36:39], v[190:193], v[142:145], v[36:39]
	v_mfma_f32_16x16x32_bf16 v[112:115], v[190:193], v[158:161], v[112:115]
	v_mfma_f32_16x16x32_bf16 v[28:31], v[210:213], v[142:145], v[28:31]
	v_mfma_f32_16x16x32_bf16 v[100:103], v[210:213], v[158:161], v[100:103]
	v_mfma_f32_16x16x32_bf16 v[24:27], v[218:221], v[142:145], v[24:27]
	v_mfma_f32_16x16x32_bf16 v[88:91], v[218:221], v[158:161], v[88:91]
	v_mfma_f32_16x16x32_bf16 v[40:43], v[186:189], v[154:157], v[40:43]
	v_mfma_f32_16x16x32_bf16 v[124:127], v[186:189], v[162:165], v[124:127]
	v_mfma_f32_16x16x32_bf16 v[36:39], v[194:197], v[154:157], v[36:39]
	v_mfma_f32_16x16x32_bf16 v[112:115], v[194:197], v[162:165], v[112:115]
	v_mfma_f32_16x16x32_bf16 v[28:31], v[214:217], v[154:157], v[28:31]
	v_mfma_f32_16x16x32_bf16 v[100:103], v[214:217], v[162:165], v[100:103]
	v_mfma_f32_16x16x32_bf16 v[24:27], v[222:225], v[154:157], v[24:27]
	v_mfma_f32_16x16x32_bf16 v[88:91], v[222:225], v[162:165], v[88:91]
	v_mfma_f32_16x16x32_bf16 v[120:123], v[182:185], v[166:169], v[120:123]
	v_mfma_f32_16x16x32_bf16 v[116:119], v[182:185], v[174:177], v[116:119]
	v_mfma_f32_16x16x32_bf16 v[108:111], v[190:193], v[166:169], v[108:111]
	v_mfma_f32_16x16x32_bf16 v[104:107], v[190:193], v[174:177], v[104:107]
	v_mfma_f32_16x16x32_bf16 v[96:99], v[210:213], v[166:169], v[96:99]
	v_mfma_f32_16x16x32_bf16 v[92:95], v[210:213], v[174:177], v[92:95]
	v_mfma_f32_16x16x32_bf16 v[84:87], v[218:221], v[166:169], v[84:87]
	v_mfma_f32_16x16x32_bf16 v[80:83], v[218:221], v[174:177], v[80:83]
	v_mfma_f32_16x16x32_bf16 v[120:123], v[186:189], v[170:173], v[120:123]
	v_mfma_f32_16x16x32_bf16 v[116:119], v[186:189], v[178:181], v[116:119]
	v_mfma_f32_16x16x32_bf16 v[108:111], v[194:197], v[170:173], v[108:111]
	v_mfma_f32_16x16x32_bf16 v[104:107], v[194:197], v[178:181], v[104:107]
	v_mfma_f32_16x16x32_bf16 v[96:99], v[214:217], v[170:173], v[96:99]
	v_mfma_f32_16x16x32_bf16 v[92:95], v[214:217], v[178:181], v[92:95]
	v_mfma_f32_16x16x32_bf16 v[84:87], v[222:225], v[170:173], v[84:87]
	v_mfma_f32_16x16x32_bf16 v[80:83], v[222:225], v[178:181], v[80:83]
	s_barrier
	s_add_i32 s66, s58, s47
	v_lshl_add_u64 v[146:147], s[38:39], 0, v[130:131]
	s_mov_b32 m0, s66
	ds_read_b128 v[182:185], v153 offset:16384
	ds_read_b128 v[186:189], v153 offset:17408
	ds_read_b128 v[190:193], v153 offset:18432
	ds_read_b128 v[194:197], v153 offset:19456
	ds_read_b128 v[210:213], v153 offset:20480
	ds_read_b128 v[214:217], v153 offset:21504
	ds_read_b128 v[218:221], v153 offset:22528
	ds_read_b128 v[222:225], v153 offset:23552
	global_load_lds_dwordx4 v[146:147], off
	s_add_i32 m0, s66, 0x2000
	s_add_u32 s66, s38, 0x80000
	v_lshl_add_u64 v[198:199], s[38:39], 0, v[128:129]
	s_addc_u32 s67, s39, 0
	s_add_i32 s68, s59, s47
	global_load_lds_dwordx4 v[198:199], off
	v_lshl_add_u64 v[226:227], s[66:67], 0, v[130:131]
	s_mov_b32 m0, s68
	v_lshl_add_u64 v[228:229], s[40:41], 0, v[128:129]
	global_load_lds_dwordx4 v[226:227], off
	v_lshl_add_u64 v[226:227], s[66:67], 0, v[128:129]
	s_add_i32 m0, s68, 0x2000
	s_nop 0
	global_load_lds_dwordx4 v[226:227], off
	v_lshl_add_u64 v[226:227], s[40:41], 0, v[130:131]
	s_mov_b32 m0, s21
	s_nop 0
	global_load_lds_dwordx4 v[226:227], off
	s_mov_b32 m0, s50
	s_nop 0
	global_load_lds_dwordx4 v[228:229], off
	s_waitcnt vmcnt(8)
	s_waitcnt lgkmcnt(0)
	s_barrier
	s_waitcnt lgkmcnt(0)
	v_mfma_f32_16x16x32_bf16 v[12:15], v[182:185], v[142:145], v[12:15]
	v_mfma_f32_16x16x32_bf16 v[76:79], v[182:185], v[158:161], v[76:79]
	v_mfma_f32_16x16x32_bf16 v[8:11], v[190:193], v[142:145], v[8:11]
	v_mfma_f32_16x16x32_bf16 v[64:67], v[190:193], v[158:161], v[64:67]
	v_mfma_f32_16x16x32_bf16 v[4:7], v[210:213], v[142:145], v[4:7]
	v_mfma_f32_16x16x32_bf16 v[52:55], v[210:213], v[158:161], v[52:55]
	v_mfma_f32_16x16x32_bf16 v[0:3], v[218:221], v[142:145], v[0:3]
	v_mfma_f32_16x16x32_bf16 v[32:35], v[218:221], v[158:161], v[32:35]
	v_mfma_f32_16x16x32_bf16 v[12:15], v[186:189], v[154:157], v[12:15]
	v_mfma_f32_16x16x32_bf16 v[76:79], v[186:189], v[162:165], v[76:79]
	v_mfma_f32_16x16x32_bf16 v[8:11], v[194:197], v[154:157], v[8:11]
	v_mfma_f32_16x16x32_bf16 v[64:67], v[194:197], v[162:165], v[64:67]
	v_mfma_f32_16x16x32_bf16 v[4:7], v[214:217], v[154:157], v[4:7]
	v_mfma_f32_16x16x32_bf16 v[52:55], v[214:217], v[162:165], v[52:55]
	v_mfma_f32_16x16x32_bf16 v[0:3], v[222:225], v[154:157], v[0:3]
	v_mfma_f32_16x16x32_bf16 v[32:35], v[222:225], v[162:165], v[32:35]
	v_mfma_f32_16x16x32_bf16 v[72:75], v[182:185], v[166:169], v[72:75]
	v_mfma_f32_16x16x32_bf16 v[68:71], v[182:185], v[174:177], v[68:71]
	v_mfma_f32_16x16x32_bf16 v[60:63], v[190:193], v[166:169], v[60:63]
	v_mfma_f32_16x16x32_bf16 v[56:59], v[190:193], v[174:177], v[56:59]
	v_mfma_f32_16x16x32_bf16 v[48:51], v[210:213], v[166:169], v[48:51]
	v_mfma_f32_16x16x32_bf16 v[44:47], v[210:213], v[174:177], v[44:47]
	v_mfma_f32_16x16x32_bf16 v[20:23], v[218:221], v[166:169], v[20:23]
	v_mfma_f32_16x16x32_bf16 v[16:19], v[218:221], v[174:177], v[16:19]
	v_mfma_f32_16x16x32_bf16 v[72:75], v[186:189], v[170:173], v[72:75]
	v_mfma_f32_16x16x32_bf16 v[68:71], v[186:189], v[178:181], v[68:71]
	v_mfma_f32_16x16x32_bf16 v[60:63], v[194:197], v[170:173], v[60:63]
	v_mfma_f32_16x16x32_bf16 v[56:59], v[194:197], v[178:181], v[56:59]
	v_mfma_f32_16x16x32_bf16 v[48:51], v[214:217], v[170:173], v[48:51]
	v_mfma_f32_16x16x32_bf16 v[44:47], v[214:217], v[178:181], v[44:47]
	v_mfma_f32_16x16x32_bf16 v[20:23], v[222:225], v[170:173], v[20:23]
	v_mfma_f32_16x16x32_bf16 v[16:19], v[222:225], v[178:181], v[16:19]
	s_barrier
	s_add_i32 s66, 0, 0x18000
	s_add_i32 s67, 0, 0x1c000
	v_add_u32_e32 v162, s66, v148
	v_add_u32_e32 v178, s67, v148
	ds_read_b128 v[142:145], v162
	ds_read_b128 v[154:157], v162 offset:1024
	ds_read_b128 v[158:161], v162 offset:2048
	ds_read_b128 v[162:165], v162 offset:3072
	ds_read_b128 v[166:169], v178
	ds_read_b128 v[170:173], v178 offset:1024
	ds_read_b128 v[174:177], v178 offset:2048
	ds_read_b128 v[178:181], v178 offset:3072
	s_add_u32 s40, s40, 0x80000
	s_addc_u32 s41, s41, 0
	s_mov_b32 m0, s51
	v_lshl_add_u64 v[230:231], s[40:41], 0, v[130:131]
	ds_read_b128 v[182:185], v153 offset:32768
	ds_read_b128 v[186:189], v153 offset:33792
	ds_read_b128 v[190:193], v153 offset:34816
	ds_read_b128 v[194:197], v153 offset:35840
	ds_read_b128 v[210:213], v153 offset:36864
	ds_read_b128 v[214:217], v153 offset:37888
	ds_read_b128 v[218:221], v153 offset:38912
	ds_read_b128 v[222:225], v153 offset:39936
	global_load_lds_dwordx4 v[230:231], off
	v_lshl_add_u64 v[230:231], s[40:41], 0, v[128:129]
	s_mov_b32 m0, s54
	s_nop 0
	global_load_lds_dwordx4 v[230:231], off
	s_waitcnt vmcnt(8)
	s_waitcnt lgkmcnt(0)
	s_barrier
	s_waitcnt lgkmcnt(0)
	v_mfma_f32_16x16x32_bf16 v[40:43], v[182:185], v[142:145], v[40:43]
	v_mfma_f32_16x16x32_bf16 v[124:127], v[182:185], v[158:161], v[124:127]
	v_mfma_f32_16x16x32_bf16 v[36:39], v[190:193], v[142:145], v[36:39]
	v_mfma_f32_16x16x32_bf16 v[112:115], v[190:193], v[158:161], v[112:115]
	v_mfma_f32_16x16x32_bf16 v[28:31], v[210:213], v[142:145], v[28:31]
	v_mfma_f32_16x16x32_bf16 v[100:103], v[210:213], v[158:161], v[100:103]
	v_mfma_f32_16x16x32_bf16 v[24:27], v[218:221], v[142:145], v[24:27]
	v_mfma_f32_16x16x32_bf16 v[88:91], v[218:221], v[158:161], v[88:91]
	v_mfma_f32_16x16x32_bf16 v[40:43], v[186:189], v[154:157], v[40:43]
	v_mfma_f32_16x16x32_bf16 v[124:127], v[186:189], v[162:165], v[124:127]
	v_mfma_f32_16x16x32_bf16 v[36:39], v[194:197], v[154:157], v[36:39]
	v_mfma_f32_16x16x32_bf16 v[112:115], v[194:197], v[162:165], v[112:115]
	v_mfma_f32_16x16x32_bf16 v[28:31], v[214:217], v[154:157], v[28:31]
	v_mfma_f32_16x16x32_bf16 v[100:103], v[214:217], v[162:165], v[100:103]
	v_mfma_f32_16x16x32_bf16 v[24:27], v[222:225], v[154:157], v[24:27]
	v_mfma_f32_16x16x32_bf16 v[88:91], v[222:225], v[162:165], v[88:91]
	v_mfma_f32_16x16x32_bf16 v[120:123], v[182:185], v[166:169], v[120:123]
	v_mfma_f32_16x16x32_bf16 v[116:119], v[182:185], v[174:177], v[116:119]
	v_mfma_f32_16x16x32_bf16 v[108:111], v[190:193], v[166:169], v[108:111]
	v_mfma_f32_16x16x32_bf16 v[104:107], v[190:193], v[174:177], v[104:107]
	v_mfma_f32_16x16x32_bf16 v[96:99], v[210:213], v[166:169], v[96:99]
	v_mfma_f32_16x16x32_bf16 v[92:95], v[210:213], v[174:177], v[92:95]
	v_mfma_f32_16x16x32_bf16 v[84:87], v[218:221], v[166:169], v[84:87]
	v_mfma_f32_16x16x32_bf16 v[80:83], v[218:221], v[174:177], v[80:83]
	v_mfma_f32_16x16x32_bf16 v[120:123], v[186:189], v[170:173], v[120:123]
	v_mfma_f32_16x16x32_bf16 v[116:119], v[186:189], v[178:181], v[116:119]
	v_mfma_f32_16x16x32_bf16 v[108:111], v[194:197], v[170:173], v[108:111]
	v_mfma_f32_16x16x32_bf16 v[104:107], v[194:197], v[178:181], v[104:107]
	v_mfma_f32_16x16x32_bf16 v[96:99], v[214:217], v[170:173], v[96:99]
	v_mfma_f32_16x16x32_bf16 v[92:95], v[214:217], v[178:181], v[92:95]
	v_mfma_f32_16x16x32_bf16 v[84:87], v[222:225], v[170:173], v[84:87]
	v_mfma_f32_16x16x32_bf16 v[80:83], v[222:225], v[178:181], v[80:83]
	s_barrier
	s_add_i32 s40, s66, s47
	v_lshl_add_u64 v[146:147], v[146:147], 0, s[18:19]
	s_mov_b32 m0, s40
	ds_read_b128 v[182:185], v153 offset:49152
	ds_read_b128 v[186:189], v153 offset:50176
	ds_read_b128 v[190:193], v153 offset:51200
	ds_read_b128 v[194:197], v153 offset:52224
	ds_read_b128 v[210:213], v153 offset:53248
	ds_read_b128 v[214:217], v153 offset:54272
	ds_read_b128 v[218:221], v153 offset:55296
	ds_read_b128 v[222:225], v153 offset:56320
	global_load_lds_dwordx4 v[146:147], off
	s_add_i32 m0, s40, 0x2000
	s_add_u32 s38, s38, 0x80080
	v_lshl_add_u64 v[146:147], v[198:199], 0, s[18:19]
	s_addc_u32 s39, s39, 0
	s_add_i32 s40, s67, s47
	global_load_lds_dwordx4 v[146:147], off
	v_lshl_add_u64 v[146:147], s[38:39], 0, v[130:131]
	s_mov_b32 m0, s40
	s_nop 0
	global_load_lds_dwordx4 v[146:147], off
	v_lshl_add_u64 v[146:147], s[38:39], 0, v[128:129]
	s_add_i32 m0, s40, 0x2000
	s_nop 0
	global_load_lds_dwordx4 v[146:147], off
	v_lshl_add_u64 v[146:147], v[226:227], 0, s[18:19]
	s_mov_b32 m0, s56
	s_nop 0
	global_load_lds_dwordx4 v[146:147], off
	v_lshl_add_u64 v[146:147], v[228:229], 0, s[18:19]
	s_mov_b32 m0, s57
	s_nop 0
	global_load_lds_dwordx4 v[146:147], off
	s_waitcnt vmcnt(8)
	s_waitcnt lgkmcnt(0)
	s_barrier
	s_waitcnt lgkmcnt(0)
	v_mfma_f32_16x16x32_bf16 v[12:15], v[182:185], v[142:145], v[12:15]
	v_mfma_f32_16x16x32_bf16 v[76:79], v[182:185], v[158:161], v[76:79]
	v_mfma_f32_16x16x32_bf16 v[8:11], v[190:193], v[142:145], v[8:11]
	v_mfma_f32_16x16x32_bf16 v[64:67], v[190:193], v[158:161], v[64:67]
	v_mfma_f32_16x16x32_bf16 v[4:7], v[210:213], v[142:145], v[4:7]
	v_mfma_f32_16x16x32_bf16 v[52:55], v[210:213], v[158:161], v[52:55]
	v_mfma_f32_16x16x32_bf16 v[0:3], v[218:221], v[142:145], v[0:3]
	v_mfma_f32_16x16x32_bf16 v[32:35], v[218:221], v[158:161], v[32:35]
	v_mfma_f32_16x16x32_bf16 v[12:15], v[186:189], v[154:157], v[12:15]
	v_mfma_f32_16x16x32_bf16 v[76:79], v[186:189], v[162:165], v[76:79]
	v_mfma_f32_16x16x32_bf16 v[8:11], v[194:197], v[154:157], v[8:11]
	v_mfma_f32_16x16x32_bf16 v[64:67], v[194:197], v[162:165], v[64:67]
	v_mfma_f32_16x16x32_bf16 v[4:7], v[214:217], v[154:157], v[4:7]
	v_mfma_f32_16x16x32_bf16 v[52:55], v[214:217], v[162:165], v[52:55]
	v_mfma_f32_16x16x32_bf16 v[0:3], v[222:225], v[154:157], v[0:3]
	v_mfma_f32_16x16x32_bf16 v[32:35], v[222:225], v[162:165], v[32:35]
	v_mfma_f32_16x16x32_bf16 v[72:75], v[182:185], v[166:169], v[72:75]
	v_mfma_f32_16x16x32_bf16 v[68:71], v[182:185], v[174:177], v[68:71]
	v_mfma_f32_16x16x32_bf16 v[60:63], v[190:193], v[166:169], v[60:63]
	v_mfma_f32_16x16x32_bf16 v[56:59], v[190:193], v[174:177], v[56:59]
	v_mfma_f32_16x16x32_bf16 v[48:51], v[210:213], v[166:169], v[48:51]
	v_mfma_f32_16x16x32_bf16 v[44:47], v[210:213], v[174:177], v[44:47]
	v_mfma_f32_16x16x32_bf16 v[20:23], v[218:221], v[166:169], v[20:23]
	v_mfma_f32_16x16x32_bf16 v[16:19], v[218:221], v[174:177], v[16:19]
	v_mfma_f32_16x16x32_bf16 v[72:75], v[186:189], v[170:173], v[72:75]
	v_mfma_f32_16x16x32_bf16 v[68:71], v[186:189], v[178:181], v[68:71]
	v_mfma_f32_16x16x32_bf16 v[60:63], v[194:197], v[170:173], v[60:63]
	v_mfma_f32_16x16x32_bf16 v[56:59], v[194:197], v[178:181], v[56:59]
	v_mfma_f32_16x16x32_bf16 v[48:51], v[214:217], v[170:173], v[48:51]
	v_mfma_f32_16x16x32_bf16 v[44:47], v[214:217], v[178:181], v[44:47]
	v_mfma_f32_16x16x32_bf16 v[20:23], v[222:225], v[170:173], v[20:23]
	v_mfma_f32_16x16x32_bf16 v[16:19], v[222:225], v[178:181], v[16:19]
	s_barrier
	s_add_i32 s65, s65, 2
	s_add_u32 s63, s63, 0x100
	s_addc_u32 s64, s64, 0
	s_add_u32 s36, s36, 0x100
	s_addc_u32 s37, s37, 0
	s_cmp_gt_u32 s65, 29
	s_cbranch_scc0 .LBB0_676
	s_setprio 0
	s_and_b64 vcc, exec, s[22:23]
	s_cbranch_vccnz .LBB0_681
	s_cmp_eq_u32 s60, 8
	s_mov_b64 s[36:37], -1
	s_cbranch_scc0 .LBB0_682

.LBB0_705:
	s_ashr_i32 s23, s22, 31
	s_lshl_b64 s[24:25], s[22:23], 20
	s_add_u32 s24, s4, s24
	s_addc_u32 s25, s5, s25
	s_and_b64 s[26:27], s[6:7], exec
	s_cselect_b32 s23, s25, s31
	s_cselect_b32 s48, s24, s30
	s_ashr_i32 s11, s10, 31
	s_lshl_b64 s[26:27], s[10:11], 20
	s_add_u32 s26, s36, s26
	s_addc_u32 s27, s37, s27
	s_and_b64 s[34:35], s[6:7], exec
	s_cselect_b32 s11, s27, s29
	s_cselect_b32 s49, s26, s28
	s_add_u32 s50, s28, 0x100
	s_addc_u32 s51, s29, 0
	s_add_u32 s28, s30, 0x80080
	v_mov_b32_e32 v16, 0
	s_addc_u32 s29, s31, 0
	s_mov_b32 s54, -2
	v_mov_b32_e32 v17, v16
	v_mov_b32_e32 v18, v16
	v_mov_b32_e32 v19, v16
	v_mov_b32_e32 v20, v16
	v_mov_b32_e32 v21, v16
	v_mov_b32_e32 v22, v16
	v_mov_b32_e32 v23, v16
	v_mov_b32_e32 v32, v16
	v_mov_b32_e32 v33, v16
	v_mov_b32_e32 v34, v16
	v_mov_b32_e32 v35, v16
	v_mov_b32_e32 v40, v16
	v_mov_b32_e32 v41, v16
	v_mov_b32_e32 v42, v16
	v_mov_b32_e32 v43, v16
	v_mov_b32_e32 v56, v16
	v_mov_b32_e32 v57, v16
	v_mov_b32_e32 v58, v16
	v_mov_b32_e32 v59, v16
	v_mov_b32_e32 v60, v16
	v_mov_b32_e32 v61, v16
	v_mov_b32_e32 v62, v16
	v_mov_b32_e32 v63, v16
	v_mov_b32_e32 v68, v16
	v_mov_b32_e32 v69, v16
	v_mov_b32_e32 v70, v16
	v_mov_b32_e32 v71, v16
	v_mov_b32_e32 v72, v16
	v_mov_b32_e32 v73, v16
	v_mov_b32_e32 v74, v16
	v_mov_b32_e32 v75, v16
	v_mov_b32_e32 v28, v16
	v_mov_b32_e32 v29, v16
	v_mov_b32_e32 v30, v16
	v_mov_b32_e32 v31, v16
	v_mov_b32_e32 v0, v16
	v_mov_b32_e32 v1, v16
	v_mov_b32_e32 v2, v16
	v_mov_b32_e32 v3, v16
	v_mov_b32_e32 v52, v16
	v_mov_b32_e32 v53, v16
	v_mov_b32_e32 v54, v16
	v_mov_b32_e32 v55, v16
	v_mov_b32_e32 v4, v16
	v_mov_b32_e32 v5, v16
	v_mov_b32_e32 v6, v16
	v_mov_b32_e32 v7, v16
	v_mov_b32_e32 v64, v16
	v_mov_b32_e32 v65, v16
	v_mov_b32_e32 v66, v16
	v_mov_b32_e32 v67, v16
	v_mov_b32_e32 v8, v16
	v_mov_b32_e32 v9, v16
	v_mov_b32_e32 v10, v16
	v_mov_b32_e32 v11, v16
	v_mov_b32_e32 v76, v16
	v_mov_b32_e32 v77, v16
	v_mov_b32_e32 v78, v16
	v_mov_b32_e32 v79, v16
	v_mov_b32_e32 v12, v16
	v_mov_b32_e32 v13, v16
	v_mov_b32_e32 v14, v16
	v_mov_b32_e32 v15, v16
	v_mov_b32_e32 v80, v16
	v_mov_b32_e32 v81, v16
	v_mov_b32_e32 v82, v16
	v_mov_b32_e32 v83, v16
	v_mov_b32_e32 v84, v16
	v_mov_b32_e32 v85, v16
	v_mov_b32_e32 v86, v16
	v_mov_b32_e32 v87, v16
	v_mov_b32_e32 v92, v16
	v_mov_b32_e32 v93, v16
	v_mov_b32_e32 v94, v16
	v_mov_b32_e32 v95, v16
	v_mov_b32_e32 v96, v16
	v_mov_b32_e32 v97, v16
	v_mov_b32_e32 v98, v16
	v_mov_b32_e32 v99, v16
	v_mov_b32_e32 v104, v16
	v_mov_b32_e32 v105, v16
	v_mov_b32_e32 v106, v16
	v_mov_b32_e32 v107, v16
	v_mov_b32_e32 v108, v16
	v_mov_b32_e32 v109, v16
	v_mov_b32_e32 v110, v16
	v_mov_b32_e32 v111, v16
	v_mov_b32_e32 v116, v16
	v_mov_b32_e32 v117, v16
	v_mov_b32_e32 v118, v16
	v_mov_b32_e32 v119, v16
	v_mov_b32_e32 v120, v16
	v_mov_b32_e32 v121, v16
	v_mov_b32_e32 v122, v16
	v_mov_b32_e32 v123, v16
	v_mov_b32_e32 v88, v16
	v_mov_b32_e32 v89, v16
	v_mov_b32_e32 v90, v16
	v_mov_b32_e32 v91, v16
	v_mov_b32_e32 v24, v16
	v_mov_b32_e32 v25, v16
	v_mov_b32_e32 v26, v16
	v_mov_b32_e32 v27, v16
	v_mov_b32_e32 v100, v16
	v_mov_b32_e32 v101, v16
	v_mov_b32_e32 v102, v16
	v_mov_b32_e32 v103, v16
	v_mov_b32_e32 v36, v16
	v_mov_b32_e32 v37, v16
	v_mov_b32_e32 v38, v16
	v_mov_b32_e32 v39, v16
	v_mov_b32_e32 v112, v16
	v_mov_b32_e32 v113, v16
	v_mov_b32_e32 v114, v16
	v_mov_b32_e32 v115, v16
	v_mov_b32_e32 v44, v16
	v_mov_b32_e32 v45, v16
	v_mov_b32_e32 v46, v16
	v_mov_b32_e32 v47, v16
	v_mov_b32_e32 v124, v16
	v_mov_b32_e32 v125, v16
	v_mov_b32_e32 v126, v16
	v_mov_b32_e32 v127, v16
	v_mov_b32_e32 v48, v16
	v_mov_b32_e32 v49, v16
	v_mov_b32_e32 v50, v16
	v_mov_b32_e32 v51, v16
	v_readfirstlane_b32 s99, v201
	s_cmp_lt_u32 s99, 0x100
	s_cbranch_scc1 .Lprio_skip5
	s_setprio 1
.Lprio_skip5:
.LBB0_706:
	ds_read_b128 v[150:153], v147
	ds_read_b128 v[154:157], v147 offset:1024
	ds_read_b128 v[158:161], v147 offset:2048
	ds_read_b128 v[162:165], v147 offset:3072
	ds_read_b128 v[166:169], v148
	ds_read_b128 v[170:173], v148 offset:1024
	ds_read_b128 v[174:177], v148 offset:2048
	ds_read_b128 v[178:181], v148 offset:3072
	s_add_u32 s30, s28, 0xfff80080
	s_addc_u32 s31, s29, -1
	s_cmp_eq_u32 s54, 28
	s_cselect_b32 s35, s23, s31
	s_cselect_b32 s34, s48, s30
	s_cselect_b32 s31, s11, s51
	s_cselect_b32 s30, s49, s50
	v_lshl_add_u64 v[142:143], s[28:29], 0, v[136:137]
	s_add_i32 m0, s17, 0xc000
	ds_read_b128 v[182:185], v149
	ds_read_b128 v[186:189], v149 offset:1024
	ds_read_b128 v[190:193], v149 offset:2048
	ds_read_b128 v[194:197], v149 offset:3072
	ds_read_b128 v[210:213], v149 offset:4096
	ds_read_b128 v[214:217], v149 offset:5120
	ds_read_b128 v[218:221], v149 offset:6144
	ds_read_b128 v[222:225], v149 offset:7168
	global_load_lds_dwordx4 v[142:143], off
	v_lshl_add_u64 v[142:143], s[28:29], 0, v[134:135]
	s_add_i32 m0, s17, 0xe000
	s_nop 0
	global_load_lds_dwordx4 v[142:143], off
	s_waitcnt vmcnt(8)
	s_waitcnt lgkmcnt(0)
	s_barrier
	s_waitcnt lgkmcnt(0)
	v_mfma_f32_16x16x32_bf16 v[48:51], v[182:185], v[150:153], v[48:51]
	v_mfma_f32_16x16x32_bf16 v[124:127], v[182:185], v[158:161], v[124:127]
	v_mfma_f32_16x16x32_bf16 v[44:47], v[190:193], v[150:153], v[44:47]
	v_mfma_f32_16x16x32_bf16 v[112:115], v[190:193], v[158:161], v[112:115]
	v_mfma_f32_16x16x32_bf16 v[36:39], v[210:213], v[150:153], v[36:39]
	v_mfma_f32_16x16x32_bf16 v[100:103], v[210:213], v[158:161], v[100:103]
	v_mfma_f32_16x16x32_bf16 v[24:27], v[218:221], v[150:153], v[24:27]
	v_mfma_f32_16x16x32_bf16 v[88:91], v[218:221], v[158:161], v[88:91]
	v_mfma_f32_16x16x32_bf16 v[48:51], v[186:189], v[154:157], v[48:51]
	v_mfma_f32_16x16x32_bf16 v[124:127], v[186:189], v[162:165], v[124:127]
	v_mfma_f32_16x16x32_bf16 v[44:47], v[194:197], v[154:157], v[44:47]
	v_mfma_f32_16x16x32_bf16 v[112:115], v[194:197], v[162:165], v[112:115]
	v_mfma_f32_16x16x32_bf16 v[36:39], v[214:217], v[154:157], v[36:39]
	v_mfma_f32_16x16x32_bf16 v[100:103], v[214:217], v[162:165], v[100:103]
	v_mfma_f32_16x16x32_bf16 v[24:27], v[222:225], v[154:157], v[24:27]
	v_mfma_f32_16x16x32_bf16 v[88:91], v[222:225], v[162:165], v[88:91]
	v_mfma_f32_16x16x32_bf16 v[120:123], v[182:185], v[166:169], v[120:123]
	v_mfma_f32_16x16x32_bf16 v[116:119], v[182:185], v[174:177], v[116:119]
	v_mfma_f32_16x16x32_bf16 v[108:111], v[190:193], v[166:169], v[108:111]
	v_mfma_f32_16x16x32_bf16 v[104:107], v[190:193], v[174:177], v[104:107]
	v_mfma_f32_16x16x32_bf16 v[96:99], v[210:213], v[166:169], v[96:99]
	v_mfma_f32_16x16x32_bf16 v[92:95], v[210:213], v[174:177], v[92:95]
	v_mfma_f32_16x16x32_bf16 v[84:87], v[218:221], v[166:169], v[84:87]
	v_mfma_f32_16x16x32_bf16 v[80:83], v[218:221], v[174:177], v[80:83]
	v_mfma_f32_16x16x32_bf16 v[120:123], v[186:189], v[170:173], v[120:123]
	v_mfma_f32_16x16x32_bf16 v[116:119], v[186:189], v[178:181], v[116:119]
	v_mfma_f32_16x16x32_bf16 v[108:111], v[194:197], v[170:173], v[108:111]
	v_mfma_f32_16x16x32_bf16 v[104:107], v[194:197], v[178:181], v[104:107]
	v_mfma_f32_16x16x32_bf16 v[96:99], v[214:217], v[170:173], v[96:99]
	v_mfma_f32_16x16x32_bf16 v[92:95], v[214:217], v[178:181], v[92:95]
	v_mfma_f32_16x16x32_bf16 v[84:87], v[222:225], v[170:173], v[84:87]
	v_mfma_f32_16x16x32_bf16 v[80:83], v[222:225], v[178:181], v[80:83]
	s_barrier
	s_add_i32 s55, s45, s38
	v_lshl_add_u64 v[142:143], s[30:31], 0, v[128:129]
	s_mov_b32 m0, s55
	ds_read_b128 v[182:185], v149 offset:16384
	ds_read_b128 v[186:189], v149 offset:17408
	ds_read_b128 v[190:193], v149 offset:18432
	ds_read_b128 v[194:197], v149 offset:19456
	ds_read_b128 v[210:213], v149 offset:20480
	ds_read_b128 v[214:217], v149 offset:21504
	ds_read_b128 v[218:221], v149 offset:22528
	ds_read_b128 v[222:225], v149 offset:23552
	global_load_lds_dwordx4 v[142:143], off
	s_add_i32 m0, s55, 0x2000
	s_add_u32 s56, s30, 0x80000
	v_lshl_add_u64 v[198:199], s[30:31], 0, v[130:131]
	s_addc_u32 s57, s31, 0
	s_add_i32 s55, s46, s38
	global_load_lds_dwordx4 v[198:199], off
	v_lshl_add_u64 v[226:227], s[56:57], 0, v[128:129]
	s_mov_b32 m0, s55
	v_lshl_add_u64 v[228:229], s[34:35], 0, v[130:131]
	global_load_lds_dwordx4 v[226:227], off
	v_lshl_add_u64 v[226:227], s[56:57], 0, v[130:131]
	s_add_i32 m0, s55, 0x2000
	s_nop 0
	global_load_lds_dwordx4 v[226:227], off
	v_lshl_add_u64 v[226:227], s[34:35], 0, v[128:129]
	s_mov_b32 m0, s17
	s_nop 0
	global_load_lds_dwordx4 v[226:227], off
	s_mov_b32 m0, s39
	s_nop 0
	global_load_lds_dwordx4 v[228:229], off
	s_waitcnt vmcnt(8)
	s_waitcnt lgkmcnt(0)
	s_barrier
	s_waitcnt lgkmcnt(0)
	v_mfma_f32_16x16x32_bf16 v[12:15], v[182:185], v[150:153], v[12:15]
	v_mfma_f32_16x16x32_bf16 v[76:79], v[182:185], v[158:161], v[76:79]
	v_mfma_f32_16x16x32_bf16 v[8:11], v[190:193], v[150:153], v[8:11]
	v_mfma_f32_16x16x32_bf16 v[64:67], v[190:193], v[158:161], v[64:67]
	v_mfma_f32_16x16x32_bf16 v[4:7], v[210:213], v[150:153], v[4:7]
	v_mfma_f32_16x16x32_bf16 v[52:55], v[210:213], v[158:161], v[52:55]
	v_mfma_f32_16x16x32_bf16 v[0:3], v[218:221], v[150:153], v[0:3]
	v_mfma_f32_16x16x32_bf16 v[28:31], v[218:221], v[158:161], v[28:31]
	v_mfma_f32_16x16x32_bf16 v[12:15], v[186:189], v[154:157], v[12:15]
	v_mfma_f32_16x16x32_bf16 v[76:79], v[186:189], v[162:165], v[76:79]
	v_mfma_f32_16x16x32_bf16 v[8:11], v[194:197], v[154:157], v[8:11]
	v_mfma_f32_16x16x32_bf16 v[64:67], v[194:197], v[162:165], v[64:67]
	v_mfma_f32_16x16x32_bf16 v[4:7], v[214:217], v[154:157], v[4:7]
	v_mfma_f32_16x16x32_bf16 v[52:55], v[214:217], v[162:165], v[52:55]
	v_mfma_f32_16x16x32_bf16 v[0:3], v[222:225], v[154:157], v[0:3]
	v_mfma_f32_16x16x32_bf16 v[28:31], v[222:225], v[162:165], v[28:31]
	v_mfma_f32_16x16x32_bf16 v[72:75], v[182:185], v[166:169], v[72:75]
	v_mfma_f32_16x16x32_bf16 v[68:71], v[182:185], v[174:177], v[68:71]
	v_mfma_f32_16x16x32_bf16 v[60:63], v[190:193], v[166:169], v[60:63]
	v_mfma_f32_16x16x32_bf16 v[56:59], v[190:193], v[174:177], v[56:59]
	v_mfma_f32_16x16x32_bf16 v[40:43], v[210:213], v[166:169], v[40:43]
	v_mfma_f32_16x16x32_bf16 v[32:35], v[210:213], v[174:177], v[32:35]
	v_mfma_f32_16x16x32_bf16 v[20:23], v[218:221], v[166:169], v[20:23]
	v_mfma_f32_16x16x32_bf16 v[16:19], v[218:221], v[174:177], v[16:19]
	v_mfma_f32_16x16x32_bf16 v[72:75], v[186:189], v[170:173], v[72:75]
	v_mfma_f32_16x16x32_bf16 v[68:71], v[186:189], v[178:181], v[68:71]
	v_mfma_f32_16x16x32_bf16 v[60:63], v[194:197], v[170:173], v[60:63]
	v_mfma_f32_16x16x32_bf16 v[56:59], v[194:197], v[178:181], v[56:59]
	v_mfma_f32_16x16x32_bf16 v[40:43], v[214:217], v[170:173], v[40:43]
	v_mfma_f32_16x16x32_bf16 v[32:35], v[214:217], v[178:181], v[32:35]
	v_mfma_f32_16x16x32_bf16 v[20:23], v[222:225], v[170:173], v[20:23]
	v_mfma_f32_16x16x32_bf16 v[16:19], v[222:225], v[178:181], v[16:19]
	s_barrier
	s_add_i32 s55, 0, 0x18000
	s_add_i32 s56, 0, 0x1c000
	v_add_u32_e32 v162, s55, v144
	v_add_u32_e32 v178, s56, v144
	ds_read_b128 v[150:153], v162
	ds_read_b128 v[154:157], v162 offset:1024
	ds_read_b128 v[158:161], v162 offset:2048
	ds_read_b128 v[162:165], v162 offset:3072
	ds_read_b128 v[166:169], v178
	ds_read_b128 v[170:173], v178 offset:1024
	ds_read_b128 v[174:177], v178 offset:2048
	ds_read_b128 v[178:181], v178 offset:3072
	s_add_u32 s34, s34, 0x80000
	s_addc_u32 s35, s35, 0
	s_mov_b32 m0, s40
	v_lshl_add_u64 v[230:231], s[34:35], 0, v[128:129]
	ds_read_b128 v[182:185], v149 offset:32768
	ds_read_b128 v[186:189], v149 offset:33792
	ds_read_b128 v[190:193], v149 offset:34816
	ds_read_b128 v[194:197], v149 offset:35840
	ds_read_b128 v[210:213], v149 offset:36864
	ds_read_b128 v[214:217], v149 offset:37888
	ds_read_b128 v[218:221], v149 offset:38912
	ds_read_b128 v[222:225], v149 offset:39936
	global_load_lds_dwordx4 v[230:231], off
	v_lshl_add_u64 v[230:231], s[34:35], 0, v[130:131]
	s_mov_b32 m0, s41
	s_nop 0
	global_load_lds_dwordx4 v[230:231], off
	s_waitcnt vmcnt(8)
	s_waitcnt lgkmcnt(0)
	s_barrier
	s_waitcnt lgkmcnt(0)
	v_mfma_f32_16x16x32_bf16 v[48:51], v[182:185], v[150:153], v[48:51]
	v_mfma_f32_16x16x32_bf16 v[124:127], v[182:185], v[158:161], v[124:127]
	v_mfma_f32_16x16x32_bf16 v[44:47], v[190:193], v[150:153], v[44:47]
	v_mfma_f32_16x16x32_bf16 v[112:115], v[190:193], v[158:161], v[112:115]
	v_mfma_f32_16x16x32_bf16 v[36:39], v[210:213], v[150:153], v[36:39]
	v_mfma_f32_16x16x32_bf16 v[100:103], v[210:213], v[158:161], v[100:103]
	v_mfma_f32_16x16x32_bf16 v[24:27], v[218:221], v[150:153], v[24:27]
	v_mfma_f32_16x16x32_bf16 v[88:91], v[218:221], v[158:161], v[88:91]
	v_mfma_f32_16x16x32_bf16 v[48:51], v[186:189], v[154:157], v[48:51]
	v_mfma_f32_16x16x32_bf16 v[124:127], v[186:189], v[162:165], v[124:127]
	v_mfma_f32_16x16x32_bf16 v[44:47], v[194:197], v[154:157], v[44:47]
	v_mfma_f32_16x16x32_bf16 v[112:115], v[194:197], v[162:165], v[112:115]
	v_mfma_f32_16x16x32_bf16 v[36:39], v[214:217], v[154:157], v[36:39]
	v_mfma_f32_16x16x32_bf16 v[100:103], v[214:217], v[162:165], v[100:103]
	v_mfma_f32_16x16x32_bf16 v[24:27], v[222:225], v[154:157], v[24:27]
	v_mfma_f32_16x16x32_bf16 v[88:91], v[222:225], v[162:165], v[88:91]
	v_mfma_f32_16x16x32_bf16 v[120:123], v[182:185], v[166:169], v[120:123]
	v_mfma_f32_16x16x32_bf16 v[116:119], v[182:185], v[174:177], v[116:119]
	v_mfma_f32_16x16x32_bf16 v[108:111], v[190:193], v[166:169], v[108:111]
	v_mfma_f32_16x16x32_bf16 v[104:107], v[190:193], v[174:177], v[104:107]
	v_mfma_f32_16x16x32_bf16 v[96:99], v[210:213], v[166:169], v[96:99]
	v_mfma_f32_16x16x32_bf16 v[92:95], v[210:213], v[174:177], v[92:95]
	v_mfma_f32_16x16x32_bf16 v[84:87], v[218:221], v[166:169], v[84:87]
	v_mfma_f32_16x16x32_bf16 v[80:83], v[218:221], v[174:177], v[80:83]
	v_mfma_f32_16x16x32_bf16 v[120:123], v[186:189], v[170:173], v[120:123]
	v_mfma_f32_16x16x32_bf16 v[116:119], v[186:189], v[178:181], v[116:119]
	v_mfma_f32_16x16x32_bf16 v[108:111], v[194:197], v[170:173], v[108:111]
	v_mfma_f32_16x16x32_bf16 v[104:107], v[194:197], v[178:181], v[104:107]
	v_mfma_f32_16x16x32_bf16 v[96:99], v[214:217], v[170:173], v[96:99]
	v_mfma_f32_16x16x32_bf16 v[92:95], v[214:217], v[178:181], v[92:95]
	v_mfma_f32_16x16x32_bf16 v[84:87], v[222:225], v[170:173], v[84:87]
	v_mfma_f32_16x16x32_bf16 v[80:83], v[222:225], v[178:181], v[80:83]
	s_barrier
	s_add_i32 s34, s55, s38
	v_lshl_add_u64 v[142:143], v[142:143], 0, s[14:15]
	s_mov_b32 m0, s34
	ds_read_b128 v[182:185], v149 offset:49152
	ds_read_b128 v[186:189], v149 offset:50176
	ds_read_b128 v[190:193], v149 offset:51200
	ds_read_b128 v[194:197], v149 offset:52224
	ds_read_b128 v[210:213], v149 offset:53248
	ds_read_b128 v[214:217], v149 offset:54272
	ds_read_b128 v[218:221], v149 offset:55296
	ds_read_b128 v[222:225], v149 offset:56320
	global_load_lds_dwordx4 v[142:143], off
	s_add_i32 m0, s34, 0x2000
	s_add_u32 s30, s30, 0x80080
	v_lshl_add_u64 v[142:143], v[198:199], 0, s[14:15]
	s_addc_u32 s31, s31, 0
	s_add_i32 s34, s56, s38
	global_load_lds_dwordx4 v[142:143], off
	v_lshl_add_u64 v[142:143], s[30:31], 0, v[128:129]
	s_mov_b32 m0, s34
	s_nop 0
	global_load_lds_dwordx4 v[142:143], off
	v_lshl_add_u64 v[142:143], s[30:31], 0, v[130:131]
	s_add_i32 m0, s34, 0x2000
	s_nop 0
	global_load_lds_dwordx4 v[142:143], off
	v_lshl_add_u64 v[142:143], v[226:227], 0, s[14:15]
	s_mov_b32 m0, s43
	s_nop 0
	global_load_lds_dwordx4 v[142:143], off
	v_lshl_add_u64 v[142:143], v[228:229], 0, s[14:15]
	s_mov_b32 m0, s44
	s_nop 0
	global_load_lds_dwordx4 v[142:143], off
	s_waitcnt vmcnt(8)
	s_waitcnt lgkmcnt(0)
	s_barrier
	s_waitcnt lgkmcnt(0)
	v_mfma_f32_16x16x32_bf16 v[12:15], v[182:185], v[150:153], v[12:15]
	v_mfma_f32_16x16x32_bf16 v[76:79], v[182:185], v[158:161], v[76:79]
	v_mfma_f32_16x16x32_bf16 v[8:11], v[190:193], v[150:153], v[8:11]
	v_mfma_f32_16x16x32_bf16 v[64:67], v[190:193], v[158:161], v[64:67]
	v_mfma_f32_16x16x32_bf16 v[4:7], v[210:213], v[150:153], v[4:7]
	v_mfma_f32_16x16x32_bf16 v[52:55], v[210:213], v[158:161], v[52:55]
	v_mfma_f32_16x16x32_bf16 v[0:3], v[218:221], v[150:153], v[0:3]
	v_mfma_f32_16x16x32_bf16 v[28:31], v[218:221], v[158:161], v[28:31]
	v_mfma_f32_16x16x32_bf16 v[12:15], v[186:189], v[154:157], v[12:15]
	v_mfma_f32_16x16x32_bf16 v[76:79], v[186:189], v[162:165], v[76:79]
	v_mfma_f32_16x16x32_bf16 v[8:11], v[194:197], v[154:157], v[8:11]
	v_mfma_f32_16x16x32_bf16 v[64:67], v[194:197], v[162:165], v[64:67]
	v_mfma_f32_16x16x32_bf16 v[4:7], v[214:217], v[154:157], v[4:7]
	v_mfma_f32_16x16x32_bf16 v[52:55], v[214:217], v[162:165], v[52:55]
	v_mfma_f32_16x16x32_bf16 v[0:3], v[222:225], v[154:157], v[0:3]
	v_mfma_f32_16x16x32_bf16 v[28:31], v[222:225], v[162:165], v[28:31]
	v_mfma_f32_16x16x32_bf16 v[72:75], v[182:185], v[166:169], v[72:75]
	v_mfma_f32_16x16x32_bf16 v[68:71], v[182:185], v[174:177], v[68:71]
	v_mfma_f32_16x16x32_bf16 v[60:63], v[190:193], v[166:169], v[60:63]
	v_mfma_f32_16x16x32_bf16 v[56:59], v[190:193], v[174:177], v[56:59]
	v_mfma_f32_16x16x32_bf16 v[40:43], v[210:213], v[166:169], v[40:43]
	v_mfma_f32_16x16x32_bf16 v[32:35], v[210:213], v[174:177], v[32:35]
	v_mfma_f32_16x16x32_bf16 v[20:23], v[218:221], v[166:169], v[20:23]
	v_mfma_f32_16x16x32_bf16 v[16:19], v[218:221], v[174:177], v[16:19]
	v_mfma_f32_16x16x32_bf16 v[72:75], v[186:189], v[170:173], v[72:75]
	v_mfma_f32_16x16x32_bf16 v[68:71], v[186:189], v[178:181], v[68:71]
	v_mfma_f32_16x16x32_bf16 v[60:63], v[194:197], v[170:173], v[60:63]
	v_mfma_f32_16x16x32_bf16 v[56:59], v[194:197], v[178:181], v[56:59]
	v_mfma_f32_16x16x32_bf16 v[40:43], v[214:217], v[170:173], v[40:43]
	v_mfma_f32_16x16x32_bf16 v[32:35], v[214:217], v[178:181], v[32:35]
	v_mfma_f32_16x16x32_bf16 v[20:23], v[222:225], v[170:173], v[20:23]
	v_mfma_f32_16x16x32_bf16 v[16:19], v[222:225], v[178:181], v[16:19]
	s_barrier
	s_add_i32 s54, s54, 2
	s_add_u32 s50, s50, 0x100
	s_addc_u32 s51, s51, 0
	s_add_u32 s28, s28, 0x100
	s_addc_u32 s29, s29, 0
	s_cmp_gt_u32 s54, 29
	s_cbranch_scc0 .LBB0_706
	s_setprio 0
	s_and_b64 vcc, exec, s[18:19]
	s_cbranch_vccnz .LBB0_711
	s_cmp_eq_u32 s47, 8
	s_mov_b64 s[28:29], -1
	s_cbranch_scc0 .LBB0_712

.LBB0_1061:
	s_ashr_i32 s19, s18, 31
	s_lshl_b64 s[20:21], s[18:19], 20
	s_add_u32 s20, s0, s20
	s_addc_u32 s21, s1, s21
	s_and_b64 s[22:23], s[4:5], exec
	s_cselect_b32 s19, s21, s29
	s_cselect_b32 s47, s20, s28
	s_ashr_i32 s17, s16, 31
	s_lshl_b64 s[22:23], s[16:17], 20
	s_add_u32 s22, s34, s22
	s_addc_u32 s23, s35, s23
	s_and_b64 s[30:31], s[4:5], exec
	s_cselect_b32 s17, s23, s27
	s_cselect_b32 s48, s22, s26
	s_add_u32 s49, s26, 0x100
	s_addc_u32 s50, s27, 0
	s_add_u32 s26, s28, 0x80080
	v_mov_b32_e32 v0, 0
	s_addc_u32 s27, s29, 0
	s_mov_b32 s51, -2
	v_mov_b32_e32 v1, v0
	v_mov_b32_e32 v2, v0
	v_mov_b32_e32 v3, v0
	v_mov_b32_e32 v4, v0
	v_mov_b32_e32 v5, v0
	v_mov_b32_e32 v6, v0
	v_mov_b32_e32 v7, v0
	v_mov_b32_e32 v12, v0
	v_mov_b32_e32 v13, v0
	v_mov_b32_e32 v14, v0
	v_mov_b32_e32 v15, v0
	v_mov_b32_e32 v20, v0
	v_mov_b32_e32 v21, v0
	v_mov_b32_e32 v22, v0
	v_mov_b32_e32 v23, v0
	v_mov_b32_e32 v28, v0
	v_mov_b32_e32 v29, v0
	v_mov_b32_e32 v30, v0
	v_mov_b32_e32 v31, v0
	v_mov_b32_e32 v36, v0
	v_mov_b32_e32 v37, v0
	v_mov_b32_e32 v38, v0
	v_mov_b32_e32 v39, v0
	v_mov_b32_e32 v44, v0
	v_mov_b32_e32 v45, v0
	v_mov_b32_e32 v46, v0
	v_mov_b32_e32 v47, v0
	v_mov_b32_e32 v52, v0
	v_mov_b32_e32 v53, v0
	v_mov_b32_e32 v54, v0
	v_mov_b32_e32 v55, v0
	v_mov_b32_e32 v8, v0
	v_mov_b32_e32 v9, v0
	v_mov_b32_e32 v10, v0
	v_mov_b32_e32 v11, v0
	v_mov_b32_e32 v16, v0
	v_mov_b32_e32 v17, v0
	v_mov_b32_e32 v18, v0
	v_mov_b32_e32 v19, v0
	v_mov_b32_e32 v24, v0
	v_mov_b32_e32 v25, v0
	v_mov_b32_e32 v26, v0
	v_mov_b32_e32 v27, v0
	v_mov_b32_e32 v32, v0
	v_mov_b32_e32 v33, v0
	v_mov_b32_e32 v34, v0
	v_mov_b32_e32 v35, v0
	v_mov_b32_e32 v40, v0
	v_mov_b32_e32 v41, v0
	v_mov_b32_e32 v42, v0
	v_mov_b32_e32 v43, v0
	v_mov_b32_e32 v48, v0
	v_mov_b32_e32 v49, v0
	v_mov_b32_e32 v50, v0
	v_mov_b32_e32 v51, v0
	v_mov_b32_e32 v56, v0
	v_mov_b32_e32 v57, v0
	v_mov_b32_e32 v58, v0
	v_mov_b32_e32 v59, v0
	v_mov_b32_e32 v60, v0
	v_mov_b32_e32 v61, v0
	v_mov_b32_e32 v62, v0
	v_mov_b32_e32 v63, v0
	v_mov_b32_e32 v64, v0
	v_mov_b32_e32 v65, v0
	v_mov_b32_e32 v66, v0
	v_mov_b32_e32 v67, v0
	v_mov_b32_e32 v68, v0
	v_mov_b32_e32 v69, v0
	v_mov_b32_e32 v70, v0
	v_mov_b32_e32 v71, v0
	v_mov_b32_e32 v76, v0
	v_mov_b32_e32 v77, v0
	v_mov_b32_e32 v78, v0
	v_mov_b32_e32 v79, v0
	v_mov_b32_e32 v84, v0
	v_mov_b32_e32 v85, v0
	v_mov_b32_e32 v86, v0
	v_mov_b32_e32 v87, v0
	v_mov_b32_e32 v92, v0
	v_mov_b32_e32 v93, v0
	v_mov_b32_e32 v94, v0
	v_mov_b32_e32 v95, v0
	v_mov_b32_e32 v100, v0
	v_mov_b32_e32 v101, v0
	v_mov_b32_e32 v102, v0
	v_mov_b32_e32 v103, v0
	v_mov_b32_e32 v108, v0
	v_mov_b32_e32 v109, v0
	v_mov_b32_e32 v110, v0
	v_mov_b32_e32 v111, v0
	v_mov_b32_e32 v116, v0
	v_mov_b32_e32 v117, v0
	v_mov_b32_e32 v118, v0
	v_mov_b32_e32 v119, v0
	v_mov_b32_e32 v72, v0
	v_mov_b32_e32 v73, v0
	v_mov_b32_e32 v74, v0
	v_mov_b32_e32 v75, v0
	v_mov_b32_e32 v80, v0
	v_mov_b32_e32 v81, v0
	v_mov_b32_e32 v82, v0
	v_mov_b32_e32 v83, v0
	v_mov_b32_e32 v88, v0
	v_mov_b32_e32 v89, v0
	v_mov_b32_e32 v90, v0
	v_mov_b32_e32 v91, v0
	v_mov_b32_e32 v96, v0
	v_mov_b32_e32 v97, v0
	v_mov_b32_e32 v98, v0
	v_mov_b32_e32 v99, v0
	v_mov_b32_e32 v104, v0
	v_mov_b32_e32 v105, v0
	v_mov_b32_e32 v106, v0
	v_mov_b32_e32 v107, v0
	v_mov_b32_e32 v112, v0
	v_mov_b32_e32 v113, v0
	v_mov_b32_e32 v114, v0
	v_mov_b32_e32 v115, v0
	v_mov_b32_e32 v120, v0
	v_mov_b32_e32 v121, v0
	v_mov_b32_e32 v122, v0
	v_mov_b32_e32 v123, v0
	v_mov_b32_e32 v124, v0
	v_mov_b32_e32 v125, v0
	v_mov_b32_e32 v126, v0
	v_mov_b32_e32 v127, v0
	v_readfirstlane_b32 s99, v201
	s_cmp_lt_u32 s99, 0x100
	s_cbranch_scc1 .Lprio_skip6
	s_setprio 1
.Lprio_skip6:
.LBB0_1062:
	ds_read_b128 v[140:143], v147
	ds_read_b128 v[150:153], v147 offset:1024
	ds_read_b128 v[154:157], v147 offset:2048
	ds_read_b128 v[158:161], v147 offset:3072
	ds_read_b128 v[162:165], v148
	ds_read_b128 v[166:169], v148 offset:1024
	ds_read_b128 v[170:173], v148 offset:2048
	ds_read_b128 v[174:177], v148 offset:3072
	s_add_u32 s28, s26, 0xfff80080
	s_addc_u32 s29, s27, -1
	s_cmp_eq_u32 s51, 28
	s_cselect_b32 s31, s19, s29
	s_cselect_b32 s30, s47, s28
	s_cselect_b32 s29, s17, s50
	s_cselect_b32 s28, s48, s49
	v_lshl_add_u64 v[198:199], s[26:27], 0, v[134:135]
	s_add_i32 m0, s25, 0xc000
	ds_read_b128 v[178:181], v149
	ds_read_b128 v[182:185], v149 offset:1024
	ds_read_b128 v[186:189], v149 offset:2048
	ds_read_b128 v[190:193], v149 offset:3072
	ds_read_b128 v[194:197], v149 offset:4096
	ds_read_b128 v[210:213], v149 offset:5120
	ds_read_b128 v[214:217], v149 offset:6144
	ds_read_b128 v[218:221], v149 offset:7168
	ds_read_b128 v[246:249], v209
	ds_read_b128 v[250:253], v209 offset:1024
	global_load_lds_dwordx4 v[198:199], off
	v_lshl_add_u64 v[198:199], s[26:27], 0, v[132:133]
	s_add_i32 m0, s25, 0xe000
	s_nop 0
	global_load_lds_dwordx4 v[198:199], off
	s_waitcnt vmcnt(9)
	s_waitcnt lgkmcnt(0)
	s_barrier
	s_waitcnt lgkmcnt(0)
	v_mfma_f32_16x16x32_bf16 v[124:127], v[140:143], v[178:181], v[124:127]
	v_mfma_f32_16x16x32_bf16 v[120:123], v[154:157], v[178:181], v[120:123]
	v_mfma_f32_16x16x32_bf16 v[112:115], v[140:143], v[186:189], v[112:115]
	v_mfma_f32_16x16x32_bf16 v[104:107], v[154:157], v[186:189], v[104:107]
	v_mfma_f32_16x16x32_bf16 v[96:99], v[140:143], v[194:197], v[96:99]
	v_mfma_f32_16x16x32_bf16 v[88:91], v[154:157], v[194:197], v[88:91]
	v_mfma_f32_16x16x32_bf16 v[80:83], v[140:143], v[214:217], v[80:83]
	v_mfma_f32_16x16x32_bf16 v[72:75], v[154:157], v[214:217], v[72:75]
	v_mfma_f32_16x16x32_bf16 v[124:127], v[150:153], v[182:185], v[124:127]
	v_mfma_f32_16x16x32_bf16 v[120:123], v[158:161], v[182:185], v[120:123]
	v_mfma_f32_16x16x32_bf16 v[112:115], v[150:153], v[190:193], v[112:115]
	v_mfma_f32_16x16x32_bf16 v[104:107], v[158:161], v[190:193], v[104:107]
	v_mfma_f32_16x16x32_bf16 v[96:99], v[150:153], v[210:213], v[96:99]
	v_mfma_f32_16x16x32_bf16 v[88:91], v[158:161], v[210:213], v[88:91]
	v_mfma_f32_16x16x32_bf16 v[80:83], v[150:153], v[218:221], v[80:83]
	v_mfma_f32_16x16x32_bf16 v[72:75], v[158:161], v[218:221], v[72:75]
	v_mfma_f32_16x16x32_bf16 v[230:233], v[140:143], v[246:249], v[230:233]
	v_mfma_f32_16x16x32_bf16 v[234:237], v[154:157], v[246:249], v[234:237]
	v_mfma_f32_16x16x32_bf16 v[230:233], v[150:153], v[250:253], v[230:233]
	v_mfma_f32_16x16x32_bf16 v[234:237], v[158:161], v[250:253], v[234:237]
	v_mfma_f32_16x16x32_bf16 v[116:119], v[162:165], v[178:181], v[116:119]
	v_mfma_f32_16x16x32_bf16 v[108:111], v[170:173], v[178:181], v[108:111]
	v_mfma_f32_16x16x32_bf16 v[100:103], v[162:165], v[186:189], v[100:103]
	v_mfma_f32_16x16x32_bf16 v[92:95], v[170:173], v[186:189], v[92:95]
	v_mfma_f32_16x16x32_bf16 v[84:87], v[162:165], v[194:197], v[84:87]
	v_mfma_f32_16x16x32_bf16 v[76:79], v[170:173], v[194:197], v[76:79]
	v_mfma_f32_16x16x32_bf16 v[68:71], v[162:165], v[214:217], v[68:71]
	v_mfma_f32_16x16x32_bf16 v[64:67], v[170:173], v[214:217], v[64:67]
	v_mfma_f32_16x16x32_bf16 v[116:119], v[166:169], v[182:185], v[116:119]
	v_mfma_f32_16x16x32_bf16 v[108:111], v[174:177], v[182:185], v[108:111]
	v_mfma_f32_16x16x32_bf16 v[100:103], v[166:169], v[190:193], v[100:103]
	v_mfma_f32_16x16x32_bf16 v[92:95], v[174:177], v[190:193], v[92:95]
	v_mfma_f32_16x16x32_bf16 v[84:87], v[166:169], v[210:213], v[84:87]
	v_mfma_f32_16x16x32_bf16 v[76:79], v[174:177], v[210:213], v[76:79]
	v_mfma_f32_16x16x32_bf16 v[68:71], v[166:169], v[218:221], v[68:71]
	v_mfma_f32_16x16x32_bf16 v[64:67], v[174:177], v[218:221], v[64:67]
	v_mfma_f32_16x16x32_bf16 v[238:241], v[162:165], v[246:249], v[238:241]
	v_mfma_f32_16x16x32_bf16 v[242:245], v[170:173], v[246:249], v[242:245]
	v_mfma_f32_16x16x32_bf16 v[238:241], v[166:169], v[250:253], v[238:241]
	v_mfma_f32_16x16x32_bf16 v[242:245], v[174:177], v[250:253], v[242:245]
	s_barrier
	s_add_u32 s60, s26, 0x80080
	s_addc_u32 s61, s27, 0
	s_mov_b32 exec_lo, 0xffff
	s_mov_b32 exec_hi, 0
	s_mov_b32 m0, s66
	s_nop 0
	global_load_lds_dwordx4 v254, s[60:61]
	s_mov_b64 exec, -1
	s_add_i32 s54, s43, s36
	v_lshl_add_u64 v[198:199], s[28:29], 0, v[130:131]
	s_mov_b32 m0, s54
	ds_read_b128 v[178:181], v149 offset:16384
	ds_read_b128 v[182:185], v149 offset:17408
	ds_read_b128 v[186:189], v149 offset:18432
	ds_read_b128 v[190:193], v149 offset:19456
	ds_read_b128 v[194:197], v149 offset:20480
	ds_read_b128 v[210:213], v149 offset:21504
	ds_read_b128 v[214:217], v149 offset:22528
	ds_read_b128 v[218:221], v149 offset:23552
	global_load_lds_dwordx4 v[198:199], off
	s_add_i32 m0, s54, 0x2000
	s_add_u32 s54, s28, 0x80000
	v_lshl_add_u64 v[222:223], s[28:29], 0, v[128:129]
	s_addc_u32 s55, s29, 0
	s_add_i32 s56, s44, s36
	global_load_lds_dwordx4 v[222:223], off
	v_lshl_add_u64 v[224:225], s[54:55], 0, v[130:131]
	s_mov_b32 m0, s56
	v_lshl_add_u64 v[226:227], s[30:31], 0, v[128:129]
	global_load_lds_dwordx4 v[224:225], off
	v_lshl_add_u64 v[224:225], s[54:55], 0, v[128:129]
	s_add_i32 m0, s56, 0x2000
	s_nop 0
	global_load_lds_dwordx4 v[224:225], off
	v_lshl_add_u64 v[224:225], s[30:31], 0, v[130:131]
	s_mov_b32 m0, s25
	s_nop 0
	global_load_lds_dwordx4 v[224:225], off
	s_mov_b32 m0, s37
	s_nop 0
	global_load_lds_dwordx4 v[226:227], off
	s_waitcnt vmcnt(9)
	s_waitcnt lgkmcnt(0)
	s_barrier
	s_waitcnt lgkmcnt(0)
	v_mfma_f32_16x16x32_bf16 v[60:63], v[140:143], v[178:181], v[60:63]
	v_mfma_f32_16x16x32_bf16 v[56:59], v[154:157], v[178:181], v[56:59]
	v_mfma_f32_16x16x32_bf16 v[48:51], v[140:143], v[186:189], v[48:51]
	v_mfma_f32_16x16x32_bf16 v[40:43], v[154:157], v[186:189], v[40:43]
	v_mfma_f32_16x16x32_bf16 v[32:35], v[140:143], v[194:197], v[32:35]
	v_mfma_f32_16x16x32_bf16 v[24:27], v[154:157], v[194:197], v[24:27]
	v_mfma_f32_16x16x32_bf16 v[16:19], v[140:143], v[214:217], v[16:19]
	v_mfma_f32_16x16x32_bf16 v[8:11], v[154:157], v[214:217], v[8:11]
	v_mfma_f32_16x16x32_bf16 v[60:63], v[150:153], v[182:185], v[60:63]
	v_mfma_f32_16x16x32_bf16 v[56:59], v[158:161], v[182:185], v[56:59]
	v_mfma_f32_16x16x32_bf16 v[48:51], v[150:153], v[190:193], v[48:51]
	v_mfma_f32_16x16x32_bf16 v[40:43], v[158:161], v[190:193], v[40:43]
	v_mfma_f32_16x16x32_bf16 v[32:35], v[150:153], v[210:213], v[32:35]
	v_mfma_f32_16x16x32_bf16 v[24:27], v[158:161], v[210:213], v[24:27]
	v_mfma_f32_16x16x32_bf16 v[16:19], v[150:153], v[218:221], v[16:19]
	v_mfma_f32_16x16x32_bf16 v[8:11], v[158:161], v[218:221], v[8:11]
	v_mfma_f32_16x16x32_bf16 v[52:55], v[162:165], v[178:181], v[52:55]
	v_mfma_f32_16x16x32_bf16 v[44:47], v[170:173], v[178:181], v[44:47]
	v_mfma_f32_16x16x32_bf16 v[36:39], v[162:165], v[186:189], v[36:39]
	v_mfma_f32_16x16x32_bf16 v[28:31], v[170:173], v[186:189], v[28:31]
	v_mfma_f32_16x16x32_bf16 v[20:23], v[162:165], v[194:197], v[20:23]
	v_mfma_f32_16x16x32_bf16 v[12:15], v[170:173], v[194:197], v[12:15]
	v_mfma_f32_16x16x32_bf16 v[4:7], v[162:165], v[214:217], v[4:7]
	v_mfma_f32_16x16x32_bf16 v[0:3], v[170:173], v[214:217], v[0:3]
	v_mfma_f32_16x16x32_bf16 v[52:55], v[166:169], v[182:185], v[52:55]
	v_mfma_f32_16x16x32_bf16 v[44:47], v[174:177], v[182:185], v[44:47]
	v_mfma_f32_16x16x32_bf16 v[36:39], v[166:169], v[190:193], v[36:39]
	v_mfma_f32_16x16x32_bf16 v[28:31], v[174:177], v[190:193], v[28:31]
	v_mfma_f32_16x16x32_bf16 v[20:23], v[166:169], v[210:213], v[20:23]
	v_mfma_f32_16x16x32_bf16 v[12:15], v[174:177], v[210:213], v[12:15]
	v_mfma_f32_16x16x32_bf16 v[4:7], v[166:169], v[218:221], v[4:7]
	v_mfma_f32_16x16x32_bf16 v[0:3], v[174:177], v[218:221], v[0:3]
	s_barrier
	s_add_i32 s54, 0, 0x18000
	s_add_i32 s55, 0, 0x1c000
	v_add_u32_e32 v158, s54, v145
	v_add_u32_e32 v174, s55, v145
	ds_read_b128 v[140:143], v158
	ds_read_b128 v[150:153], v158 offset:1024
	ds_read_b128 v[154:157], v158 offset:2048
	ds_read_b128 v[158:161], v158 offset:3072
	ds_read_b128 v[162:165], v174
	ds_read_b128 v[166:169], v174 offset:1024
	ds_read_b128 v[170:173], v174 offset:2048
	ds_read_b128 v[174:177], v174 offset:3072
	s_add_u32 s30, s30, 0x80000
	s_addc_u32 s31, s31, 0
	s_mov_b32 m0, s38
	v_lshl_add_u64 v[228:229], s[30:31], 0, v[130:131]
	ds_read_b128 v[178:181], v149 offset:32768
	ds_read_b128 v[182:185], v149 offset:33792
	ds_read_b128 v[186:189], v149 offset:34816
	ds_read_b128 v[190:193], v149 offset:35840
	ds_read_b128 v[194:197], v149 offset:36864
	ds_read_b128 v[210:213], v149 offset:37888
	ds_read_b128 v[214:217], v149 offset:38912
	ds_read_b128 v[218:221], v149 offset:39936
	ds_read_b128 v[246:249], v209 offset:2048
	ds_read_b128 v[250:253], v209 offset:3072
	global_load_lds_dwordx4 v[228:229], off
	v_lshl_add_u64 v[228:229], s[30:31], 0, v[128:129]
	s_mov_b32 m0, s39
	s_nop 0
	global_load_lds_dwordx4 v[228:229], off
	s_waitcnt vmcnt(9)
	s_waitcnt lgkmcnt(0)
	s_barrier
	s_waitcnt lgkmcnt(0)
	v_mfma_f32_16x16x32_bf16 v[124:127], v[140:143], v[178:181], v[124:127]
	v_mfma_f32_16x16x32_bf16 v[120:123], v[154:157], v[178:181], v[120:123]
	v_mfma_f32_16x16x32_bf16 v[112:115], v[140:143], v[186:189], v[112:115]
	v_mfma_f32_16x16x32_bf16 v[104:107], v[154:157], v[186:189], v[104:107]
	v_mfma_f32_16x16x32_bf16 v[96:99], v[140:143], v[194:197], v[96:99]
	v_mfma_f32_16x16x32_bf16 v[88:91], v[154:157], v[194:197], v[88:91]
	v_mfma_f32_16x16x32_bf16 v[80:83], v[140:143], v[214:217], v[80:83]
	v_mfma_f32_16x16x32_bf16 v[72:75], v[154:157], v[214:217], v[72:75]
	v_mfma_f32_16x16x32_bf16 v[124:127], v[150:153], v[182:185], v[124:127]
	v_mfma_f32_16x16x32_bf16 v[120:123], v[158:161], v[182:185], v[120:123]
	v_mfma_f32_16x16x32_bf16 v[112:115], v[150:153], v[190:193], v[112:115]
	v_mfma_f32_16x16x32_bf16 v[104:107], v[158:161], v[190:193], v[104:107]
	v_mfma_f32_16x16x32_bf16 v[96:99], v[150:153], v[210:213], v[96:99]
	v_mfma_f32_16x16x32_bf16 v[88:91], v[158:161], v[210:213], v[88:91]
	v_mfma_f32_16x16x32_bf16 v[80:83], v[150:153], v[218:221], v[80:83]
	v_mfma_f32_16x16x32_bf16 v[72:75], v[158:161], v[218:221], v[72:75]
	v_mfma_f32_16x16x32_bf16 v[230:233], v[140:143], v[246:249], v[230:233]
	v_mfma_f32_16x16x32_bf16 v[234:237], v[154:157], v[246:249], v[234:237]
	v_mfma_f32_16x16x32_bf16 v[230:233], v[150:153], v[250:253], v[230:233]
	v_mfma_f32_16x16x32_bf16 v[234:237], v[158:161], v[250:253], v[234:237]
	v_mfma_f32_16x16x32_bf16 v[116:119], v[162:165], v[178:181], v[116:119]
	v_mfma_f32_16x16x32_bf16 v[108:111], v[170:173], v[178:181], v[108:111]
	v_mfma_f32_16x16x32_bf16 v[100:103], v[162:165], v[186:189], v[100:103]
	v_mfma_f32_16x16x32_bf16 v[92:95], v[170:173], v[186:189], v[92:95]
	v_mfma_f32_16x16x32_bf16 v[84:87], v[162:165], v[194:197], v[84:87]
	v_mfma_f32_16x16x32_bf16 v[76:79], v[170:173], v[194:197], v[76:79]
	v_mfma_f32_16x16x32_bf16 v[68:71], v[162:165], v[214:217], v[68:71]
	v_mfma_f32_16x16x32_bf16 v[64:67], v[170:173], v[214:217], v[64:67]
	v_mfma_f32_16x16x32_bf16 v[116:119], v[166:169], v[182:185], v[116:119]
	v_mfma_f32_16x16x32_bf16 v[108:111], v[174:177], v[182:185], v[108:111]
	v_mfma_f32_16x16x32_bf16 v[100:103], v[166:169], v[190:193], v[100:103]
	v_mfma_f32_16x16x32_bf16 v[92:95], v[174:177], v[190:193], v[92:95]
	v_mfma_f32_16x16x32_bf16 v[84:87], v[166:169], v[210:213], v[84:87]
	v_mfma_f32_16x16x32_bf16 v[76:79], v[174:177], v[210:213], v[76:79]
	v_mfma_f32_16x16x32_bf16 v[68:71], v[166:169], v[218:221], v[68:71]
	v_mfma_f32_16x16x32_bf16 v[64:67], v[174:177], v[218:221], v[64:67]
	v_mfma_f32_16x16x32_bf16 v[238:241], v[162:165], v[246:249], v[238:241]
	v_mfma_f32_16x16x32_bf16 v[242:245], v[170:173], v[246:249], v[242:245]
	v_mfma_f32_16x16x32_bf16 v[238:241], v[166:169], v[250:253], v[238:241]
	v_mfma_f32_16x16x32_bf16 v[242:245], v[174:177], v[250:253], v[242:245]
	s_barrier
	s_add_u32 s60, s26, 0x80100
	s_addc_u32 s61, s27, 0
	s_mov_b32 exec_lo, 0xffff
	s_mov_b32 exec_hi, 0
	s_add_i32 m0, s66, 0x800
	s_nop 0
	global_load_lds_dwordx4 v254, s[60:61]
	s_mov_b64 exec, -1
	s_add_i32 s30, s54, s36
	v_lshl_add_u64 v[198:199], v[198:199], 0, s[12:13]
	s_mov_b32 m0, s30
	ds_read_b128 v[178:181], v149 offset:49152
	ds_read_b128 v[182:185], v149 offset:50176
	ds_read_b128 v[186:189], v149 offset:51200
	ds_read_b128 v[190:193], v149 offset:52224
	ds_read_b128 v[194:197], v149 offset:53248
	ds_read_b128 v[210:213], v149 offset:54272
	ds_read_b128 v[214:217], v149 offset:55296
	ds_read_b128 v[218:221], v149 offset:56320
	global_load_lds_dwordx4 v[198:199], off
	s_add_i32 m0, s30, 0x2000
	s_add_u32 s28, s28, 0x80080
	v_lshl_add_u64 v[198:199], v[222:223], 0, s[12:13]
	s_addc_u32 s29, s29, 0
	s_add_i32 s30, s55, s36
	global_load_lds_dwordx4 v[198:199], off
	v_lshl_add_u64 v[198:199], s[28:29], 0, v[130:131]
	s_mov_b32 m0, s30
	s_nop 0
	global_load_lds_dwordx4 v[198:199], off
	v_lshl_add_u64 v[198:199], s[28:29], 0, v[128:129]
	s_add_i32 m0, s30, 0x2000
	s_nop 0
	global_load_lds_dwordx4 v[198:199], off
	v_lshl_add_u64 v[198:199], v[224:225], 0, s[12:13]
	s_mov_b32 m0, s41
	s_nop 0
	global_load_lds_dwordx4 v[198:199], off
	v_lshl_add_u64 v[198:199], v[226:227], 0, s[12:13]
	s_mov_b32 m0, s42
	s_nop 0
	global_load_lds_dwordx4 v[198:199], off
	s_waitcnt vmcnt(9)
	s_waitcnt lgkmcnt(0)
	s_barrier
	s_waitcnt lgkmcnt(0)
	v_mfma_f32_16x16x32_bf16 v[60:63], v[140:143], v[178:181], v[60:63]
	v_mfma_f32_16x16x32_bf16 v[56:59], v[154:157], v[178:181], v[56:59]
	v_mfma_f32_16x16x32_bf16 v[48:51], v[140:143], v[186:189], v[48:51]
	v_mfma_f32_16x16x32_bf16 v[40:43], v[154:157], v[186:189], v[40:43]
	v_mfma_f32_16x16x32_bf16 v[32:35], v[140:143], v[194:197], v[32:35]
	v_mfma_f32_16x16x32_bf16 v[24:27], v[154:157], v[194:197], v[24:27]
	v_mfma_f32_16x16x32_bf16 v[16:19], v[140:143], v[214:217], v[16:19]
	v_mfma_f32_16x16x32_bf16 v[8:11], v[154:157], v[214:217], v[8:11]
	v_mfma_f32_16x16x32_bf16 v[60:63], v[150:153], v[182:185], v[60:63]
	v_mfma_f32_16x16x32_bf16 v[56:59], v[158:161], v[182:185], v[56:59]
	v_mfma_f32_16x16x32_bf16 v[48:51], v[150:153], v[190:193], v[48:51]
	v_mfma_f32_16x16x32_bf16 v[40:43], v[158:161], v[190:193], v[40:43]
	v_mfma_f32_16x16x32_bf16 v[32:35], v[150:153], v[210:213], v[32:35]
	v_mfma_f32_16x16x32_bf16 v[24:27], v[158:161], v[210:213], v[24:27]
	v_mfma_f32_16x16x32_bf16 v[16:19], v[150:153], v[218:221], v[16:19]
	v_mfma_f32_16x16x32_bf16 v[8:11], v[158:161], v[218:221], v[8:11]
	v_mfma_f32_16x16x32_bf16 v[52:55], v[162:165], v[178:181], v[52:55]
	v_mfma_f32_16x16x32_bf16 v[44:47], v[170:173], v[178:181], v[44:47]
	v_mfma_f32_16x16x32_bf16 v[36:39], v[162:165], v[186:189], v[36:39]
	v_mfma_f32_16x16x32_bf16 v[28:31], v[170:173], v[186:189], v[28:31]
	v_mfma_f32_16x16x32_bf16 v[20:23], v[162:165], v[194:197], v[20:23]
	v_mfma_f32_16x16x32_bf16 v[12:15], v[170:173], v[194:197], v[12:15]
	v_mfma_f32_16x16x32_bf16 v[4:7], v[162:165], v[214:217], v[4:7]
	v_mfma_f32_16x16x32_bf16 v[0:3], v[170:173], v[214:217], v[0:3]
	v_mfma_f32_16x16x32_bf16 v[52:55], v[166:169], v[182:185], v[52:55]
	v_mfma_f32_16x16x32_bf16 v[44:47], v[174:177], v[182:185], v[44:47]
	v_mfma_f32_16x16x32_bf16 v[36:39], v[166:169], v[190:193], v[36:39]
	v_mfma_f32_16x16x32_bf16 v[28:31], v[174:177], v[190:193], v[28:31]
	v_mfma_f32_16x16x32_bf16 v[20:23], v[166:169], v[210:213], v[20:23]
	v_mfma_f32_16x16x32_bf16 v[12:15], v[174:177], v[210:213], v[12:15]
	v_mfma_f32_16x16x32_bf16 v[4:7], v[166:169], v[218:221], v[4:7]
	v_mfma_f32_16x16x32_bf16 v[0:3], v[174:177], v[218:221], v[0:3]
	s_barrier
	s_add_i32 s51, s51, 2
	s_add_u32 s49, s49, 0x100
	s_addc_u32 s50, s50, 0
	s_add_u32 s26, s26, 0x100
	s_addc_u32 s27, s27, 0
	s_cmp_gt_u32 s51, 29
	s_cbranch_scc0 .LBB0_1062
	s_setprio 0
	s_and_b64 vcc, exec, s[14:15]
	s_cbranch_vccz .LBB0_1065
	s_barrier

.LBB0_1068:
	s_and_b32 s60, s2, 7
	s_lshr_b32 s61, s2, 3
	s_lshl_b32 s60, s60, 3
	s_lshr_b32 s62, s61, 2
	s_add_i32 s60, s60, s62
	s_and_b32 s61, s61, 3
	s_mul_i32 s62, s60, 0x110
	s_addk_i32 s62, 0x100
	s_lshr_b32 s67, s63, 2
	s_and_b32 s68, s63, 3
	s_lshl_b32 s69, s61, 8
	s_lshl_b32 s70, s67, 7
	s_add_i32 s69, s69, s70
	s_lshl_b32 s70, s68, 5
	s_add_i32 s69, s69, s70
	s_lshl_b32 s69, s69, 2
	s_lshl_b32 s70, s62, 12
	s_add_u32 s69, s69, s70
	s_add_u32 s70, s10, s69
	s_addc_u32 s71, s11, 0
	s_add_u32 s72, s8, s69
	s_addc_u32 s73, s9, 0
	v_and_b32_e32 v0, 15, v200
	v_lshrrev_b32_e32 v2, 4, v200
	v_lshlrev_b32_e32 v0, 12, v0
	v_lshl_add_u32 v0, v2, 4, v0
	global_load_dwordx4 v[2:5], v0, s[70:71]
	global_load_dwordx4 v[6:9], v0, s[70:71] offset:64
	s_cmp_eq_u32 s67, 0
	s_cbranch_scc1 .Lslab9_wr0
	v_mov_b32_e32 v230, v238
	v_mov_b32_e32 v231, v239
	v_mov_b32_e32 v232, v240
	v_mov_b32_e32 v233, v241
	v_mov_b32_e32 v234, v242
	v_mov_b32_e32 v235, v243
	v_mov_b32_e32 v236, v244
	v_mov_b32_e32 v237, v245
